# attention unit body hand-rewritten: software-pipelined QK/softmax/PV, V image natural key order (no permlane swaps), K dist-3 / V dist-2 LDS-DMA
# speedup vs baseline: 1.0450x; 1.0450x over previous
.LBB0_237:
	v_mov_b64_e32 v[30:31], v[14:15]
	v_mov_b64_e32 v[28:29], v[12:13]
	v_mov_b64_e32 v[26:27], v[10:11]
	v_mov_b64_e32 v[24:25], v[8:9]
	v_mov_b64_e32 v[22:23], v[6:7]
	v_mov_b64_e32 v[20:21], v[4:5]
	v_mov_b64_e32 v[18:19], v[2:3]
	v_mov_b64_e32 v[16:17], v[0:1]
	global_load_dwordx2 v[64:65], v[184:185], off
	global_load_dwordx4 v[68:71], v[182:183], off offset:448
	global_load_dwordx4 v[72:75], v[182:183], off offset:464
	global_load_dwordx4 v[20:23], v[182:183], off offset:320
	global_load_dwordx4 v[16:19], v[182:183], off offset:336
	s_lshl_b32 s0, s95, 8
	s_and_b32 s96, s0, 0x3f00
	s_mul_i32 s0, s96, 0x2400
	s_add_u32 s4, s57, s0
	s_addc_u32 s5, s59, 0
	s_lshl_b32 s0, s95, 1
	s_and_b32 s66, s0, 0xffffff80
	s_ashr_i32 s67, s66, 31
	s_lshl_b64 s[0:1], s[66:67], 1
	s_add_u32 s0, s4, s0
	s_addc_u32 s1, s5, s1
	s_ashr_i32 s4, s95, 1
	s_and_b32 s4, s4, 0xffffff80
	s_ashr_i32 s5, s4, 31
	s_lshl_b64 s[68:69], s[4:5], 1
	s_add_u32 s72, s75, s68
	s_addc_u32 s73, s76, s69
	s_add_u32 s70, s77, s68
	v_readfirstlane_b32 s97, v177
	s_addc_u32 s71, s78, s69
	s_lshr_b32 s33, s97, 6
	s_lshl_b32 s8, s33, 5
	v_or_b32_e32 v26, s8, v178
	v_mov_b64_e32 v[24:25], s[0:1]
	s_movk_i32 s0, 0x2400
	v_mad_u64_u32 v[24:25], s[0:1], v26, s0, v[24:25]
	v_lshl_add_u64 v[66:67], v[24:25], 0, v[188:189]
	v_cmp_lt_i32_e64 s[0:1], v212, v211
	global_load_dwordx4 v[94:97], v[66:67], off offset:224
	global_load_dwordx4 v[98:101], v[66:67], off offset:160
	v_cndmask_b32_e64 v52, v210, v212, s[0:1]
	v_cmp_lt_i32_e64 s[0:1], v213, v211
	global_load_dwordx4 v[44:47], v[182:183], off
	global_load_dwordx4 v[40:43], v[182:183], off offset:16
	global_load_dwordx4 v[36:39], v[182:183], off offset:64
	global_load_dwordx4 v[32:35], v[182:183], off offset:80
	global_load_dwordx4 v[104:107], v[182:183], off offset:384
	global_load_dwordx4 v[122:125], v[182:183], off offset:400
	global_load_dwordx4 v[126:129], v[66:67], off offset:192
	global_load_dwordx4 v[136:139], v[66:67], off offset:128
	global_load_dwordx4 v[28:31], v[182:183], off offset:256
	global_load_dwordx4 v[24:27], v[182:183], off offset:272
	global_load_dwordx4 v[48:51], v[182:183], off offset:128
	global_load_dwordx4 v[60:63], v[182:183], off offset:144
	global_load_dwordx4 v[140:143], v[182:183], off offset:192
	global_load_dwordx4 v[144:147], v[182:183], off offset:208
	v_cndmask_b32_e64 v53, v210, v213, s[0:1]
	v_cmp_lt_i32_e64 s[0:1], v214, v211
	v_lshlrev_b32_e32 v76, 2, v52
	v_lshlrev_b32_e32 v77, 2, v53
	v_cndmask_b32_e64 v54, v210, v214, s[0:1]
	v_cmp_lt_i32_e64 s[0:1], v215, v211
	v_lshlrev_b32_e32 v78, 2, v54
	v_or_b32_e32 v134, s96, v178
	v_cndmask_b32_e64 v55, v210, v215, s[0:1]
	v_cmp_lt_i32_e64 s[0:1], v216, v211
	v_lshlrev_b32_e32 v90, 2, v55
	s_mov_b32 s4, 0x7fffffc0
	v_cndmask_b32_e64 v56, v210, v216, s[0:1]
	v_cmp_lt_i32_e64 s[0:1], v217, v211
	v_lshlrev_b32_e32 v102, 2, v56
	v_mov_b32_e32 v195, v181
	v_cndmask_b32_e64 v57, v210, v217, s[0:1]
	v_lshlrev_b32_e32 v108, 2, v57
	global_load_dwordx4 v[52:55], v[66:67], off
	global_load_dwordx4 v[148:151], v[66:67], off offset:32
	global_load_dwordx4 v[56:59], v[66:67], off offset:64
	global_load_dwordx4 v[152:155], v[66:67], off offset:96
	s_mov_b32 s0, 0x800000
	v_mov_b32_e32 v218, v181
	s_waitcnt vmcnt(24)
	v_max_f32_e64 v66, |v65|, |v65|
	v_max_f32_e64 v67, |v64|, |v64|
	s_waitcnt vmcnt(22)
	v_mov_b32_e32 v64, v74
	v_max_f32_e32 v74, v67, v66
	s_waitcnt vmcnt(20)
	v_mov_b32_e32 v65, v18
	v_mov_b32_e32 v18, v75
	ds_bpermute_b32 v75, v76, v74
	v_mov_b32_e32 v82, v70
	v_mov_b32_e32 v66, v72
	v_mov_b32_e32 v89, v20
	v_mov_b32_e32 v88, v68
	s_waitcnt lgkmcnt(0)
	v_max_f32_e32 v70, v75, v75
	v_max_f32_e32 v70, v74, v70
	ds_bpermute_b32 v72, v77, v70
	v_mov_b32_e32 v67, v16
	v_mov_b32_e32 v16, v73
	v_mov_b32_e32 v83, v22
	v_mov_b32_e32 v22, v71
	s_waitcnt lgkmcnt(0)
	v_max_f32_e32 v20, v72, v72
	v_max_f32_e32 v20, v70, v20
	ds_bpermute_b32 v68, v78, v20
	s_waitcnt vmcnt(17)
	v_mov_b32_e32 v169, v46
	s_waitcnt lgkmcnt(0)
	v_max_f32_e32 v68, v68, v68
	v_max_f32_e32 v20, v20, v68
	ds_bpermute_b32 v68, v90, v20
	s_waitcnt vmcnt(16)
	v_mov_b32_e32 v167, v40
	s_waitcnt vmcnt(15)
	v_mov_b32_e32 v163, v36
	s_waitcnt vmcnt(11)
	v_and_b32_e32 v114, 0xffff0000, v129
	v_and_b32_e32 v118, 0xffff0000, v128
	s_waitcnt lgkmcnt(0)
	v_max_f32_e32 v68, v68, v68
	v_max_f32_e32 v20, v20, v68
	ds_bpermute_b32 v68, v102, v20
	v_and_b32_e32 v78, 0xffff0000, v97
	v_and_b32_e32 v84, 0xffff0000, v96
	v_lshlrev_b32_e32 v80, 16, v97
	v_lshlrev_b32_e32 v86, 16, v96
	s_waitcnt lgkmcnt(0)
	v_max_f32_e32 v68, v68, v68
	v_max_f32_e32 v20, v20, v68
	ds_bpermute_b32 v68, v108, v20
	v_mov_b32_e32 v72, v78
	v_mov_b32_e32 v73, v84
	v_and_b32_e32 v90, 0xffff0000, v95
	v_mov_b32_e32 v70, v80
	v_mov_b32_e32 v71, v86
	v_pk_mul_f32 v[72:73], v[72:73], v[72:73]
	v_and_b32_e32 v108, 0xffff0000, v94
	v_lshlrev_b32_e32 v92, 16, v95
	v_lshlrev_b32_e32 v102, 16, v94
	v_pk_fma_f32 v[96:97], v[70:71], v[70:71], v[72:73]
	v_mov_b32_e32 v72, v90
	v_mov_b32_e32 v73, v108
	s_waitcnt lgkmcnt(0)
	v_max_f32_e32 v68, v68, v68
	v_mov_b32_e32 v70, v92
	v_mov_b32_e32 v71, v102
	v_pk_mul_f32 v[72:73], v[72:73], v[72:73]
	v_max_f32_e32 v135, v20, v68
	v_pk_fma_f32 v[94:95], v[70:71], v[70:71], v[72:73]
	v_lshlrev_b32_e32 v112, 16, v129
	v_lshlrev_b32_e32 v68, 16, v128
	v_mov_b32_e32 v72, v114
	v_mov_b32_e32 v73, v118
	v_mov_b32_e32 v70, v112
	v_mov_b32_e32 v71, v68
	v_pk_mul_f32 v[72:73], v[72:73], v[72:73]
	s_waitcnt vmcnt(10)
	v_and_b32_e32 v131, 0xffff0000, v137
	v_and_b32_e32 v130, 0xffff0000, v127
	s_waitcnt vmcnt(6)
	v_mov_b32_e32 v40, v61
	s_waitcnt vmcnt(3)
	v_lshlrev_b32_e32 v61, 16, v53
	v_and_b32_e32 v171, 0xffff0000, v53
	s_waitcnt vmcnt(1)
	v_and_b32_e32 v170, 0xffff0000, v57
	v_lshlrev_b32_e32 v173, 16, v52
	v_and_b32_e32 v53, 0xffff0000, v52
	v_and_b32_e32 v52, 0xffff0000, v56
	v_lshlrev_b32_e32 v93, 16, v99
	v_and_b32_e32 v91, 0xffff0000, v99
	v_lshlrev_b32_e32 v103, 16, v98
	v_and_b32_e32 v109, 0xffff0000, v98
	v_pk_fma_f32 v[98:99], v[70:71], v[70:71], v[72:73]
	v_lshlrev_b32_e32 v71, 16, v137
	v_lshlrev_b32_e32 v70, 16, v127
	v_pk_mul_f32 v[74:75], v[130:131], v[130:131]
	v_mov_b32_e32 v158, v144
	s_waitcnt vmcnt(0)
	v_lshlrev_b32_e32 v144, 16, v153
	v_and_b32_e32 v160, 0xffff0000, v153
	v_mov_b32_e32 v36, v141
	v_lshlrev_b32_e32 v141, 16, v55
	v_mov_b32_e32 v153, v42
	v_and_b32_e32 v165, 0xffff0000, v55
	v_mov_b32_e32 v42, v63
	v_lshlrev_b32_e32 v63, 16, v54
	v_mov_b32_e32 v166, v60
	v_and_b32_e32 v55, 0xffff0000, v54
	v_and_b32_e32 v54, 0xffff0000, v58
	v_lshlrev_b32_e32 v60, 16, v57
	v_pk_mul_f32 v[128:129], v[170:171], v[170:171]
	v_lshlrev_b32_e32 v172, 16, v56
	v_pk_mul_f32 v[56:57], v[52:53], v[52:53]
	v_lshlrev_b32_e32 v81, 16, v101
	v_and_b32_e32 v79, 0xffff0000, v101
	v_lshlrev_b32_e32 v87, 16, v100
	v_and_b32_e32 v85, 0xffff0000, v100
	v_mov_b32_e32 v20, v69
	v_lshlrev_b32_e32 v113, 16, v139
	v_and_b32_e32 v115, 0xffff0000, v139
	v_lshlrev_b32_e32 v69, 16, v138
	v_and_b32_e32 v119, 0xffff0000, v138
	v_pk_fma_f32 v[100:101], v[70:71], v[70:71], v[74:75]
	v_lshlrev_b32_e32 v75, 16, v136
	v_and_b32_e32 v133, 0xffff0000, v136
	v_lshlrev_b32_e32 v137, 16, v151
	v_lshlrev_b32_e32 v136, 16, v155
	v_mov_b32_e32 v138, v146
	v_mov_b32_e32 v139, v34
	v_and_b32_e32 v157, 0xffff0000, v151
	v_and_b32_e32 v156, 0xffff0000, v155
	v_mov_b32_e32 v34, v147
	v_lshlrev_b32_e32 v147, 16, v150
	v_lshlrev_b32_e32 v146, 16, v154
	v_mov_b32_e32 v159, v32
	v_and_b32_e32 v151, 0xffff0000, v150
	v_and_b32_e32 v150, 0xffff0000, v154
	v_mov_b32_e32 v32, v145
	v_lshlrev_b32_e32 v145, 16, v149
	v_mov_b32_e32 v154, v142
	v_mov_b32_e32 v155, v38
	v_and_b32_e32 v161, 0xffff0000, v149
	v_mov_b32_e32 v38, v143
	v_lshlrev_b32_e32 v143, 16, v148
	v_lshlrev_b32_e32 v142, 16, v152
	v_mov_b32_e32 v162, v140
	v_and_b32_e32 v149, 0xffff0000, v148
	v_and_b32_e32 v148, 0xffff0000, v152
	v_lshlrev_b32_e32 v140, 16, v59
	v_mov_b32_e32 v152, v62
	v_and_b32_e32 v164, 0xffff0000, v59
	v_lshlrev_b32_e32 v62, 16, v58
	v_pk_mul_f32 v[58:59], v[54:55], v[54:55]
	v_pk_fma_f32 v[128:129], v[60:61], v[60:61], v[128:129]
	v_pk_fma_f32 v[56:57], v[172:173], v[172:173], v[56:57]
	v_lshlrev_b32_e32 v74, 16, v126
	v_and_b32_e32 v132, 0xffff0000, v126
	v_pk_mul_f32 v[126:127], v[164:165], v[164:165]
	v_pk_fma_f32 v[58:59], v[62:63], v[62:63], v[58:59]
	v_add_f32_e32 v46, v57, v129
	v_mov_b32_e32 v116, v124
	v_mov_b32_e32 v117, v26
	v_mov_b32_e32 v26, v125
	v_pk_mul_f32 v[124:125], v[148:149], v[148:149]
	v_pk_fma_f32 v[126:127], v[140:141], v[140:141], v[126:127]
	v_add_f32_e32 v46, v59, v46
	v_mov_b32_e32 v120, v122
	v_mov_b32_e32 v121, v24
	v_mov_b32_e32 v24, v123
	v_pk_mul_f32 v[122:123], v[160:161], v[160:161]
	v_pk_fma_f32 v[124:125], v[142:143], v[142:143], v[124:125]
	v_add_f32_e32 v46, v127, v46
	v_pk_mul_f32 v[110:111], v[150:151], v[150:151]
	v_pk_fma_f32 v[122:123], v[144:145], v[144:145], v[122:123]
	v_add_f32_e32 v46, v125, v46
	v_mov_b32_e32 v76, v104
	v_mov_b32_e32 v77, v28
	v_mov_b32_e32 v28, v105
	v_pk_mul_f32 v[104:105], v[156:157], v[156:157]
	v_pk_fma_f32 v[110:111], v[146:147], v[146:147], v[110:111]
	v_add_f32_e32 v46, v123, v46
	v_pk_fma_f32 v[104:105], v[136:137], v[136:137], v[104:105]
	v_add_f32_e32 v46, v111, v46
	v_add_f32_e32 v46, v105, v46
	v_pk_add_f32 v[56:57], v[56:57], v[46:47] op_sel_hi:[1,0]
	v_mov_b32_e32 v72, v106
	v_pk_add_f32 v[56:57], v[128:129], v[56:57]
	v_mov_b32_e32 v73, v30
	v_pk_add_f32 v[56:57], v[58:59], v[56:57]
	v_mov_b32_e32 v30, v107
	v_pk_add_f32 v[56:57], v[126:127], v[56:57]
	v_pk_mul_f32 v[106:107], v[132:133], v[132:133]
	v_pk_add_f32 v[56:57], v[124:125], v[56:57]
	v_pk_fma_f32 v[106:107], v[74:75], v[74:75], v[106:107]
	v_pk_add_f32 v[56:57], v[122:123], v[56:57]
	v_mul_f32_e32 v46, v69, v69
	v_pk_add_f32 v[56:57], v[110:111], v[56:57]
	v_fmac_f32_e32 v46, v119, v119
	v_pk_add_f32 v[56:57], v[104:105], v[56:57]
	v_mov_b32_e32 v168, v50
	v_pk_add_f32 v[56:57], v[106:107], v[56:57] op_sel:[1,0] op_sel_hi:[0,1]
	v_pk_add_f32 v[56:57], v[100:101], v[56:57] op_sel:[1,0] op_sel_hi:[0,1]
	v_pk_add_f32 v[56:57], v[46:47], v[56:57] op_sel_hi:[0,1]
	v_mul_f32_e32 v46, v113, v113
	v_fmac_f32_e32 v46, v115, v115
	v_pk_add_f32 v[56:57], v[46:47], v[56:57] op_sel_hi:[0,1]
	v_mul_f32_e32 v46, v103, v103
	v_fmac_f32_e32 v46, v109, v109
	v_pk_add_f32 v[56:57], v[46:47], v[56:57] op_sel_hi:[0,1]
	v_mul_f32_e32 v46, v93, v93
	v_fmac_f32_e32 v46, v91, v91
	v_pk_add_f32 v[56:57], v[46:47], v[56:57] op_sel_hi:[0,1]
	v_mul_f32_e32 v46, v87, v87
	v_fmac_f32_e32 v46, v85, v85
	v_pk_add_f32 v[56:57], v[46:47], v[56:57] op_sel_hi:[0,1]
	v_mul_f32_e32 v46, v81, v81
	v_fmac_f32_e32 v46, v79, v79
	v_pk_add_f32 v[56:57], v[46:47], v[56:57] op_sel_hi:[0,1]
	v_pk_add_f32 v[56:57], v[106:107], v[56:57]
	s_nop 0
	v_pk_add_f32 v[56:57], v[100:101], v[56:57]
	s_nop 0
	v_pk_add_f32 v[56:57], v[98:99], v[56:57] op_sel:[1,0] op_sel_hi:[0,1]
	v_pk_add_f32 v[56:57], v[98:99], v[56:57]
	s_nop 0
	v_pk_add_f32 v[56:57], v[94:95], v[56:57] op_sel:[1,0] op_sel_hi:[0,1]
	v_pk_add_f32 v[56:57], v[94:95], v[56:57]
	s_nop 0
	v_pk_add_f32 v[56:57], v[96:97], v[56:57] op_sel:[1,0] op_sel_hi:[0,1]
	v_pk_add_f32 v[56:57], v[96:97], v[56:57]
	s_nop 0
	v_mov_b32_e32 v46, v56
	s_nop 1
	v_permlane32_swap_b32_e32 v56, v46
	v_add_f32_e32 v46, v56, v46
	v_fmamk_f32 v46, v46, 0x3c000000, v208
	v_mul_f32_e32 v50, 0x4b800000, v46
	v_cmp_gt_f32_e64 s[0:1], s0, v46
	s_nop 1
	v_cndmask_b32_e64 v46, v46, v50, s[0:1]
	v_rsq_f32_e32 v56, v46
	v_mov_b32_e32 v46, v51
	v_mov_b32_e32 v51, v44
	v_mov_b32_e32 v50, v48
	v_mul_f32_e32 v44, 0x45800000, v56
	v_cndmask_b32_e64 v174, v56, v44, s[0:1]
	v_pk_mul_f32 v[40:41], v[174:175], v[40:41] op_sel_hi:[0,1]
	v_pk_mul_f32 v[36:37], v[174:175], v[36:37] op_sel_hi:[0,1]
	v_pk_mul_f32 v[106:107], v[40:41], v[54:55]
	v_pk_mul_f32 v[40:41], v[174:175], v[152:153] op_sel_hi:[0,1]
	v_pk_mul_f32 v[96:97], v[36:37], v[148:149]
	v_pk_mul_f32 v[36:37], v[174:175], v[154:155] op_sel_hi:[0,1]
	v_pk_mul_f32 v[50:51], v[174:175], v[50:51] op_sel_hi:[0,1]
	v_mov_b32_e32 v44, v49
	v_pk_mul_f32 v[104:105], v[40:41], v[140:141]
	v_pk_mul_f32 v[40:41], v[174:175], v[42:43] op_sel_hi:[0,1]
	v_pk_mul_f32 v[94:95], v[36:37], v[144:145]
	v_pk_mul_f32 v[36:37], v[174:175], v[38:39] op_sel_hi:[0,1]
	v_pk_mul_f32 v[32:33], v[174:175], v[32:33] op_sel_hi:[0,1]
	v_pk_mul_f32 v[128:129], v[50:51], v[172:173]
	v_pk_mul_f32 v[44:45], v[174:175], v[44:45] op_sel_hi:[0,1]
	v_pk_mul_f32 v[100:101], v[40:41], v[164:165]
	v_pk_mul_f32 v[40:41], v[174:175], v[162:163] op_sel_hi:[0,1]
	v_pk_mul_f32 v[42:43], v[36:37], v[160:161]
	v_pk_mul_f32 v[36:37], v[174:175], v[158:159] op_sel_hi:[0,1]
	v_pk_mul_f32 v[38:39], v[32:33], v[150:151]
	v_pk_mul_f32 v[32:33], v[174:175], v[138:139] op_sel_hi:[0,1]
	v_pk_mul_f32 v[126:127], v[44:45], v[52:53]
	v_pk_mul_f32 v[44:45], v[174:175], v[168:169] op_sel_hi:[0,1]
	v_pk_mul_f32 v[98:99], v[40:41], v[142:143]
	v_pk_mul_f32 v[40:41], v[36:37], v[146:147]
	v_pk_mul_f32 v[36:37], v[32:33], v[136:137]
	v_pk_mul_f32 v[32:33], v[174:175], v[34:35] op_sel_hi:[0,1]
	v_mul_f32_e32 v34, v129, v129
	v_pk_mul_f32 v[124:125], v[44:45], v[60:61]
	v_pk_mul_f32 v[44:45], v[174:175], v[46:47] op_sel_hi:[0,1]
	v_fmac_f32_e32 v34, v127, v127
	v_pk_mul_f32 v[122:123], v[44:45], v[170:171]
	v_pk_mul_f32 v[44:45], v[174:175], v[166:167] op_sel_hi:[0,1]
	v_fmac_f32_e32 v34, v125, v125
	v_pk_mul_f32 v[110:111], v[44:45], v[62:63]
	v_fmac_f32_e32 v34, v123, v123
	v_fmac_f32_e32 v34, v111, v111
	v_fmac_f32_e32 v34, v107, v107
	v_fmac_f32_e32 v34, v105, v105
	v_fmac_f32_e32 v34, v101, v101
	v_fmac_f32_e32 v34, v99, v99
	v_fmac_f32_e32 v34, v97, v97
	v_fmac_f32_e32 v34, v95, v95
	v_fmac_f32_e32 v34, v43, v43
	v_fmac_f32_e32 v34, v41, v41
	v_fmac_f32_e32 v34, v39, v39
	v_pk_mul_f32 v[32:33], v[32:33], v[156:157]
	v_fmac_f32_e32 v34, v37, v37
	v_fmac_f32_e32 v34, v33, v33
	v_pk_fma_f32 v[34:35], v[128:129], v[128:129], v[34:35] op_sel_hi:[1,1,0]
	v_pk_mul_f32 v[44:45], v[174:175], v[76:77] op_sel_hi:[0,1]
	v_pk_fma_f32 v[34:35], v[126:127], v[126:127], v[34:35]
	v_pk_mul_f32 v[76:77], v[44:45], v[74:75]
	v_pk_fma_f32 v[34:35], v[124:125], v[124:125], v[34:35]
	v_pk_mul_f32 v[28:29], v[174:175], v[28:29] op_sel_hi:[0,1]
	v_pk_fma_f32 v[34:35], v[122:123], v[122:123], v[34:35]
	v_mul_f32_e32 v44, v77, v77
	v_pk_fma_f32 v[34:35], v[110:111], v[110:111], v[34:35]
	v_pk_mul_f32 v[74:75], v[28:29], v[132:133]
	v_pk_fma_f32 v[34:35], v[106:107], v[106:107], v[34:35]
	v_mul_f32_e32 v28, v75, v75
	v_pk_fma_f32 v[34:35], v[104:105], v[104:105], v[34:35]
	v_pk_mul_f32 v[30:31], v[174:175], v[30:31] op_sel_hi:[0,1]
	v_pk_fma_f32 v[34:35], v[100:101], v[100:101], v[34:35]
	v_pk_mul_f32 v[24:25], v[174:175], v[24:25] op_sel_hi:[0,1]
	v_pk_fma_f32 v[34:35], v[98:99], v[98:99], v[34:35]
	v_pk_mul_f32 v[62:63], v[24:25], v[118:119]
	v_pk_fma_f32 v[34:35], v[96:97], v[96:97], v[34:35]
	v_mul_f32_e32 v24, v63, v63
	v_pk_fma_f32 v[34:35], v[94:95], v[94:95], v[34:35]
	v_pk_mul_f32 v[26:27], v[174:175], v[26:27] op_sel_hi:[0,1]
	v_pk_fma_f32 v[34:35], v[42:43], v[42:43], v[34:35]
	v_pk_mul_f32 v[58:59], v[26:27], v[114:115]
	v_pk_fma_f32 v[34:35], v[40:41], v[40:41], v[34:35]
	v_mul_f32_e32 v26, v59, v59
	v_pk_fma_f32 v[34:35], v[38:39], v[38:39], v[34:35]
	v_pk_mul_f32 v[20:21], v[174:175], v[20:21] op_sel_hi:[0,1]
	v_pk_fma_f32 v[34:35], v[36:37], v[36:37], v[34:35]
	v_pk_mul_f32 v[54:55], v[20:21], v[108:109]
	v_pk_fma_f32 v[34:35], v[32:33], v[32:33], v[34:35]
	v_mul_f32_e32 v20, v55, v55
	v_pk_add_f32 v[34:35], v[44:45], v[34:35] op_sel_hi:[0,1]
	v_pk_add_f32 v[28:29], v[28:29], v[34:35] op_sel_hi:[0,1]
	v_pk_mul_f32 v[34:35], v[174:175], v[72:73] op_sel_hi:[0,1]
	v_pk_mul_f32 v[72:73], v[34:35], v[70:71]
	v_pk_mul_f32 v[70:71], v[30:31], v[130:131]
	v_mul_f32_e32 v34, v73, v73
	v_pk_add_f32 v[28:29], v[34:35], v[28:29] op_sel_hi:[0,1]
	v_mul_f32_e32 v30, v71, v71
	v_pk_add_f32 v[28:29], v[30:31], v[28:29] op_sel_hi:[0,1]
	v_pk_mul_f32 v[30:31], v[174:175], v[120:121] op_sel_hi:[0,1]
	v_pk_mul_f32 v[68:69], v[30:31], v[68:69]
	v_pk_mul_f32 v[22:23], v[174:175], v[22:23] op_sel_hi:[0,1]
	v_mul_f32_e32 v30, v69, v69
	v_pk_add_f32 v[28:29], v[30:31], v[28:29] op_sel_hi:[0,1]
	v_pk_add_f32 v[24:25], v[24:25], v[28:29] op_sel_hi:[0,1]
	v_pk_mul_f32 v[28:29], v[174:175], v[116:117] op_sel_hi:[0,1]
	v_pk_mul_f32 v[60:61], v[28:29], v[112:113]
	v_pk_mul_f32 v[50:51], v[22:23], v[90:91]
	v_mul_f32_e32 v28, v61, v61
	v_pk_add_f32 v[24:25], v[28:29], v[24:25] op_sel_hi:[0,1]
	v_pk_add_f32 v[24:25], v[26:27], v[24:25] op_sel_hi:[0,1]
	v_pk_mul_f32 v[26:27], v[174:175], v[88:89] op_sel_hi:[0,1]
	v_pk_mul_f32 v[56:57], v[26:27], v[102:103]
	v_mul_f32_e32 v22, v51, v51
	v_mul_f32_e32 v26, v57, v57
	v_pk_add_f32 v[24:25], v[26:27], v[24:25] op_sel_hi:[0,1]
	v_pk_add_f32 v[20:21], v[20:21], v[24:25] op_sel_hi:[0,1]
	v_pk_mul_f32 v[24:25], v[174:175], v[82:83] op_sel_hi:[0,1]
	v_pk_mul_f32 v[52:53], v[24:25], v[92:93]
	v_pk_mul_f32 v[16:17], v[174:175], v[16:17] op_sel_hi:[0,1]
	v_mul_f32_e32 v24, v53, v53
	v_pk_add_f32 v[20:21], v[24:25], v[20:21] op_sel_hi:[0,1]
	v_pk_add_f32 v[20:21], v[22:23], v[20:21] op_sel_hi:[0,1]
	v_pk_mul_f32 v[22:23], v[174:175], v[66:67] op_sel_hi:[0,1]
	v_pk_mul_f32 v[48:49], v[22:23], v[86:87]
	v_pk_mul_f32 v[46:47], v[16:17], v[84:85]
	v_mul_f32_e32 v22, v49, v49
	v_pk_add_f32 v[20:21], v[22:23], v[20:21] op_sel_hi:[0,1]
	v_mul_f32_e32 v16, v47, v47
	v_pk_add_f32 v[16:17], v[16:17], v[20:21] op_sel_hi:[0,1]
	v_pk_mul_f32 v[20:21], v[174:175], v[64:65] op_sel_hi:[0,1]
	v_pk_mul_f32 v[44:45], v[20:21], v[80:81]
	v_pk_mul_f32 v[18:19], v[174:175], v[18:19] op_sel_hi:[0,1]
	v_mul_f32_e32 v20, v45, v45
	v_pk_mul_f32 v[34:35], v[18:19], v[78:79]
	v_pk_add_f32 v[16:17], v[20:21], v[16:17] op_sel_hi:[0,1]
	v_mul_f32_e32 v18, v35, v35
	v_pk_add_f32 v[16:17], v[18:19], v[16:17] op_sel_hi:[0,1]
	v_pk_fma_f32 v[16:17], v[76:77], v[76:77], v[16:17]
	s_mov_b32 s0, 0xf800000
	v_pk_fma_f32 v[16:17], v[74:75], v[74:75], v[16:17]
	v_add_u32_e32 v108, s8, v134
	v_pk_fma_f32 v[16:17], v[72:73], v[72:73], v[16:17]
	v_and_or_b32 v180, v108, s4, v200
	v_pk_fma_f32 v[16:17], v[70:71], v[70:71], v[16:17]
	v_lshl_add_u64 v[102:103], v[180:181], 2, s[6:7]
	v_pk_fma_f32 v[16:17], v[68:69], v[68:69], v[16:17]
	v_lshlrev_b32_e32 v108, 6, v108
	v_pk_fma_f32 v[16:17], v[62:63], v[62:63], v[16:17]
	s_nop 0
	v_pk_fma_f32 v[16:17], v[60:61], v[60:61], v[16:17]
	s_nop 0
	v_pk_fma_f32 v[16:17], v[58:59], v[58:59], v[16:17]
	s_nop 0
	v_pk_fma_f32 v[16:17], v[56:57], v[56:57], v[16:17]
	s_nop 0
	v_pk_fma_f32 v[16:17], v[54:55], v[54:55], v[16:17]
	s_nop 0
	v_pk_fma_f32 v[16:17], v[52:53], v[52:53], v[16:17]
	s_nop 0
	v_pk_fma_f32 v[16:17], v[50:51], v[50:51], v[16:17]
	s_nop 0
	v_pk_fma_f32 v[16:17], v[48:49], v[48:49], v[16:17]
	s_nop 0
	v_pk_fma_f32 v[16:17], v[46:47], v[46:47], v[16:17]
	s_nop 0
	v_pk_fma_f32 v[16:17], v[44:45], v[44:45], v[16:17]
	s_nop 0
	v_pk_fma_f32 v[16:17], v[34:35], v[34:35], v[16:17]
	s_nop 0
	v_mov_b32_e32 v17, v16
	s_nop 1
	v_permlane32_swap_b32_e32 v16, v17
	v_add_f32_e32 v16, v16, v17
	v_mul_f32_e32 v17, 0x4f800000, v16
	v_cmp_gt_f32_e64 s[0:1], s0, v16
	s_nop 1
	v_cndmask_b32_e64 v16, v16, v17, s[0:1]
	v_sqrt_f32_e32 v17, v16
	s_nop 0
	v_add_u32_e32 v18, -1, v17
	v_fma_f32 v19, -v18, v17, v16
	v_cmp_ge_f32_e64 s[4:5], 0, v19
	v_add_u32_e32 v19, 1, v17
	s_nop 0
	v_cndmask_b32_e64 v18, v17, v18, s[4:5]
	v_fma_f32 v17, -v19, v17, v16
	v_cmp_lt_f32_e64 s[4:5], 0, v17
	s_nop 1
	v_cndmask_b32_e64 v17, v18, v19, s[4:5]
	v_mul_f32_e32 v18, 0x37800000, v17
	v_cndmask_b32_e64 v17, v17, v18, s[0:1]
	v_cmp_class_f32_e64 s[0:1], v16, v209
	s_movk_i32 s4, 0x4000
	s_nop 0
	v_cndmask_b32_e64 v16, v17, v16, s[0:1]
	v_mul_f32_e32 v16, 0x3e0293ee, v16
	v_mul_f32_e32 v16, 0xc13504f3, v16
	v_mul_f32_e32 v16, v16, v135
	v_mul_f32_e32 v16, 0x3f801062, v16
	v_max_f32_e32 v16, 0xc2700000, v16
	v_mov_b32_e32 v17, v16
	v_mov_b32_e32 v18, v16
	v_mov_b32_e32 v19, v16
	v_mov_b32_e32 v20, v16
	v_mov_b32_e32 v21, v16
	v_mov_b32_e32 v22, v16
	v_mov_b32_e32 v23, v16
	v_mov_b32_e32 v24, v16
	v_mov_b32_e32 v25, v16
	v_mov_b32_e32 v26, v16
	v_mov_b32_e32 v27, v16
	v_mov_b32_e32 v28, v16
	v_mov_b32_e32 v29, v16
	v_mov_b32_e32 v30, v16
	v_mov_b32_e32 v31, v16
	global_load_dwordx4 v[64:67], v[102:103], off
	global_load_dwordx4 v[78:81], v[102:103], off offset:16
	global_load_dwordx4 v[82:85], v[102:103], off offset:32
	global_load_dwordx4 v[86:89], v[102:103], off offset:48
	global_load_dwordx4 v[90:93], v[102:103], off offset:128
	global_load_dwordx4 v[112:115], v[102:103], off offset:144
	global_load_dwordx4 v[116:119], v[102:103], off offset:176
	global_load_dwordx4 v[130:133], v[102:103], off offset:160
	s_movk_i32 s0, 0xfc0
	v_and_or_b32 v108, v108, s0, v200
	v_lshlrev_b32_e32 v108, 2, v108
	s_lshr_b32 s0, s97, 3
	s_and_b32 s0, s0, 0x1ffffff0
	s_waitcnt vmcnt(7)
	v_pk_mul_f32 v[102:103], v[128:129], v[64:65] op_sel:[1,0] op_sel_hi:[0,1]
	v_pk_mul_f32 v[64:65], v[128:129], v[64:65]
	v_sub_f32_e32 v102, v102, v103
	v_add_f32_e32 v64, v64, v65
	v_mul_f32_e32 v120, 0x3e0293ee, v64
	v_pk_mul_f32 v[64:65], v[126:127], v[66:67] op_sel:[1,0] op_sel_hi:[0,1]
	v_sub_f32_e32 v64, v64, v65
	v_mul_f32_e32 v121, 0x3e0293ee, v64
	v_pk_mul_f32 v[64:65], v[126:127], v[66:67]
	v_mul_f32_e32 v109, 0x3e0293ee, v102
	v_add_f32_e32 v64, v64, v65
	v_mul_f32_e32 v126, 0x3e0293ee, v64
	s_waitcnt vmcnt(6)
	v_pk_mul_f32 v[64:65], v[124:125], v[78:79] op_sel:[1,0] op_sel_hi:[0,1]
	v_sub_f32_e32 v64, v64, v65
	v_mul_f32_e32 v127, 0x3e0293ee, v64
	v_pk_mul_f32 v[64:65], v[124:125], v[78:79]
	s_nop 0
	v_add_f32_e32 v64, v64, v65
	v_mul_f32_e32 v124, 0x3e0293ee, v64
	v_pk_mul_f32 v[64:65], v[122:123], v[80:81] op_sel:[1,0] op_sel_hi:[0,1]
	v_sub_f32_e32 v64, v64, v65
	v_mul_f32_e32 v125, 0x3e0293ee, v64
	v_pk_mul_f32 v[64:65], v[122:123], v[80:81]
	s_nop 0
	v_add_f32_e32 v102, v64, v65
	global_load_dwordx4 v[64:67], v108, s[6:7] offset:16
	global_load_dwordx4 v[78:81], v108, s[6:7]
	v_mul_f32_e32 v122, 0x3e0293ee, v102
	s_waitcnt vmcnt(7)
	v_pk_mul_f32 v[102:103], v[110:111], v[82:83] op_sel:[1,0] op_sel_hi:[0,1]
	v_pk_mul_f32 v[82:83], v[110:111], v[82:83]
	v_sub_f32_e32 v102, v102, v103
	v_add_f32_e32 v82, v82, v83
	v_mul_f32_e32 v110, 0x3e0293ee, v82
	v_pk_mul_f32 v[82:83], v[106:107], v[84:85] op_sel:[1,0] op_sel_hi:[0,1]
	v_sub_f32_e32 v82, v82, v83
	v_mul_f32_e32 v111, 0x3e0293ee, v82
	v_pk_mul_f32 v[82:83], v[106:107], v[84:85]
	v_mul_f32_e32 v123, 0x3e0293ee, v102
	v_add_f32_e32 v82, v82, v83
	v_mul_f32_e32 v106, 0x3e0293ee, v82
	s_waitcnt vmcnt(6)
	v_pk_mul_f32 v[82:83], v[104:105], v[86:87] op_sel:[1,0] op_sel_hi:[0,1]
	v_sub_f32_e32 v82, v82, v83
	v_mul_f32_e32 v107, 0x3e0293ee, v82
	v_pk_mul_f32 v[82:83], v[104:105], v[86:87]
	v_pk_mul_f32 v[86:87], v[100:101], v[88:89]
	v_add_f32_e32 v82, v82, v83
	v_mul_f32_e32 v128, 0x3e0293ee, v82
	v_pk_mul_f32 v[82:83], v[100:101], v[88:89] op_sel:[1,0] op_sel_hi:[0,1]
	v_sub_f32_e32 v82, v82, v83
	v_mul_f32_e32 v129, 0x3e0293ee, v82
	global_load_dwordx4 v[82:85], v108, s[6:7] offset:48
	global_load_dwordx4 v[102:105], v108, s[6:7] offset:32
	v_add_f32_e32 v86, v86, v87
	v_mul_f32_e32 v100, 0x3e0293ee, v86
	s_waitcnt vmcnt(7)
	v_pk_mul_f32 v[86:87], v[98:99], v[90:91] op_sel:[1,0] op_sel_hi:[0,1]
	v_sub_f32_e32 v86, v86, v87
	v_mul_f32_e32 v101, 0x3e0293ee, v86
	v_pk_mul_f32 v[86:87], v[98:99], v[90:91]
	s_nop 0
	v_add_f32_e32 v86, v86, v87
	v_mul_f32_e32 v98, 0x3e0293ee, v86
	v_pk_mul_f32 v[86:87], v[96:97], v[92:93] op_sel:[1,0] op_sel_hi:[0,1]
	v_sub_f32_e32 v86, v86, v87
	v_mul_f32_e32 v99, 0x3e0293ee, v86
	v_pk_mul_f32 v[86:87], v[96:97], v[92:93]
	s_nop 0
	v_add_f32_e32 v86, v86, v87
	v_mul_f32_e32 v96, 0x3e0293ee, v86
	s_waitcnt vmcnt(6)
	v_pk_mul_f32 v[86:87], v[94:95], v[112:113] op_sel:[1,0] op_sel_hi:[0,1]
	v_sub_f32_e32 v86, v86, v87
	v_mul_f32_e32 v97, 0x3e0293ee, v86
	v_pk_mul_f32 v[86:87], v[94:95], v[112:113]
	v_pk_mul_f32 v[94:95], v[42:43], v[114:115] op_sel:[1,0] op_sel_hi:[0,1]
	v_add_f32_e32 v86, v86, v87
	v_mul_f32_e32 v112, 0x3e0293ee, v86
	global_load_dwordx4 v[86:89], v108, s[6:7] offset:144
	global_load_dwordx4 v[90:93], v108, s[6:7] offset:128
	v_pk_mul_f32 v[42:43], v[42:43], v[114:115]
	v_sub_f32_e32 v94, v94, v95
	v_add_f32_e32 v42, v42, v43
	v_mul_f32_e32 v114, 0x3e0293ee, v42
	s_waitcnt vmcnt(6)
	v_pk_mul_f32 v[42:43], v[40:41], v[130:131] op_sel:[1,0] op_sel_hi:[0,1]
	v_pk_mul_f32 v[40:41], v[40:41], v[130:131]
	v_sub_f32_e32 v42, v42, v43
	v_add_f32_e32 v40, v40, v41
	v_mul_f32_e32 v130, 0x3e0293ee, v40
	v_pk_mul_f32 v[40:41], v[38:39], v[132:133] op_sel:[1,0] op_sel_hi:[0,1]
	v_pk_mul_f32 v[38:39], v[38:39], v[132:133]
	v_sub_f32_e32 v40, v40, v41
	v_add_f32_e32 v38, v38, v39
	v_mul_f32_e32 v132, 0x3e0293ee, v38
	v_pk_mul_f32 v[38:39], v[36:37], v[116:117] op_sel:[1,0] op_sel_hi:[0,1]
	v_sub_f32_e32 v38, v38, v39
	v_pk_mul_f32 v[36:37], v[36:37], v[116:117]
	v_mul_f32_e32 v113, 0x3e0293ee, v94
	v_mul_f32_e32 v115, 0x3e0293ee, v42
	v_mul_f32_e32 v131, 0x3e0293ee, v40
	v_mul_f32_e32 v133, 0x3e0293ee, v38
	v_add_f32_e32 v94, v36, v37
	global_load_dwordx4 v[36:39], v108, s[6:7] offset:176
	global_load_dwordx4 v[40:43], v108, s[6:7] offset:160
	v_mul_f32_e32 v108, 0x3e0293ee, v94
	v_pk_mul_f32 v[94:95], v[32:33], v[118:119] op_sel:[1,0] op_sel_hi:[0,1]
	v_pk_mul_f32 v[32:33], v[32:33], v[118:119]
	v_sub_f32_e32 v94, v94, v95
	v_add_f32_e32 v32, v32, v33
	v_mul_f32_e32 v95, 0x3e0293ee, v32
	v_mul_f32_e32 v94, 0x3e0293ee, v94
	v_cvt_pk_bf16_f32 v172, v109, v121
	s_waitcnt vmcnt(6)
	v_pk_mul_f32 v[32:33], v[76:77], v[78:79] op_sel:[1,0] op_sel_hi:[0,1]
	v_sub_f32_e32 v32, v32, v33
	v_mul_f32_e32 v116, 0x3e0293ee, v32
	v_pk_mul_f32 v[32:33], v[76:77], v[78:79]
	v_cvt_pk_bf16_f32 v173, v127, v125
	v_cvt_pk_bf16_f32 v174, v123, v111
	v_cvt_pk_bf16_f32 v175, v107, v129
	v_cvt_pk_bf16_f32 v168, v101, v99
	v_cvt_pk_bf16_f32 v169, v97, v113
	s_nop 0
	v_add_f32_e32 v32, v32, v33
	v_mul_f32_e32 v76, 0x3e0293ee, v32
	v_pk_mul_f32 v[32:33], v[74:75], v[80:81] op_sel:[1,0] op_sel_hi:[0,1]
	v_sub_f32_e32 v32, v32, v33
	v_mul_f32_e32 v77, 0x3e0293ee, v32
	v_pk_mul_f32 v[32:33], v[74:75], v[80:81]
	v_cvt_pk_bf16_f32 v170, v115, v131
	v_cvt_pk_bf16_f32 v171, v133, v94
	v_cvt_pk_bf16_f32 v164, v120, v126
	v_cvt_pk_bf16_f32 v165, v124, v122
	v_cvt_pk_bf16_f32 v166, v110, v106
	s_nop 0
	v_add_f32_e32 v32, v32, v33
	v_mul_f32_e32 v74, 0x3e0293ee, v32
	v_pk_mul_f32 v[32:33], v[72:73], v[64:65] op_sel:[1,0] op_sel_hi:[0,1]
	v_sub_f32_e32 v32, v32, v33
	v_mul_f32_e32 v75, 0x3e0293ee, v32
	v_pk_mul_f32 v[32:33], v[72:73], v[64:65]
	v_cvt_pk_bf16_f32 v167, v128, v100
	v_cvt_pk_bf16_f32 v160, v98, v96
	v_cvt_pk_bf16_f32 v161, v112, v114
	v_cvt_pk_bf16_f32 v162, v130, v132
	v_cvt_pk_bf16_f32 v163, v108, v95
	s_nop 0
	v_add_f32_e32 v32, v32, v33
	v_mul_f32_e32 v64, 0x3e0293ee, v32
	v_pk_mul_f32 v[32:33], v[70:71], v[66:67] op_sel:[1,0] op_sel_hi:[0,1]
	v_sub_f32_e32 v32, v32, v33
	v_mul_f32_e32 v65, 0x3e0293ee, v32
	v_pk_mul_f32 v[32:33], v[70:71], v[66:67]
	v_cvt_pk_bf16_f32 v156, v116, v77
	v_cvt_pk_bf16_f32 v157, v75, v65
	v_mov_b32_e32 v65, v181
	v_add_f32_e32 v32, v32, v33
	v_mul_f32_e32 v66, 0x3e0293ee, v32
	s_waitcnt vmcnt(4)
	v_pk_mul_f32 v[32:33], v[68:69], v[102:103] op_sel:[1,0] op_sel_hi:[0,1]
	v_sub_f32_e32 v32, v32, v33
	v_mul_f32_e32 v67, 0x3e0293ee, v32
	v_pk_mul_f32 v[32:33], v[68:69], v[102:103]
	v_mov_b32_e32 v70, v181
	v_add_f32_e32 v32, v32, v33
	v_mul_f32_e32 v68, 0x3e0293ee, v32
	v_pk_mul_f32 v[32:33], v[62:63], v[104:105] op_sel:[1,0] op_sel_hi:[0,1]
	v_sub_f32_e32 v32, v32, v33
	v_mul_f32_e32 v69, 0x3e0293ee, v32
	v_pk_mul_f32 v[32:33], v[62:63], v[104:105]
	v_cvt_pk_bf16_f32 v158, v67, v69
	v_mov_b32_e32 v67, v181
	v_add_f32_e32 v32, v32, v33
	v_mul_f32_e32 v62, 0x3e0293ee, v32
	v_pk_mul_f32 v[32:33], v[60:61], v[82:83] op_sel:[1,0] op_sel_hi:[0,1]
	v_sub_f32_e32 v32, v32, v33
	v_mul_f32_e32 v63, 0x3e0293ee, v32
	v_pk_mul_f32 v[32:33], v[60:61], v[82:83]
	v_mov_b32_e32 v69, v181
	v_add_f32_e32 v32, v32, v33
	v_mul_f32_e32 v60, 0x3e0293ee, v32
	v_pk_mul_f32 v[32:33], v[58:59], v[84:85] op_sel:[1,0] op_sel_hi:[0,1]
	v_sub_f32_e32 v32, v32, v33
	v_mul_f32_e32 v61, 0x3e0293ee, v32
	v_pk_mul_f32 v[32:33], v[58:59], v[84:85]
	v_cvt_pk_bf16_f32 v159, v63, v61
	v_mov_b32_e32 v61, v181
	v_add_f32_e32 v32, v32, v33
	v_mul_f32_e32 v58, 0x3e0293ee, v32
	s_waitcnt vmcnt(2)
	v_pk_mul_f32 v[32:33], v[56:57], v[90:91] op_sel:[1,0] op_sel_hi:[0,1]
	v_sub_f32_e32 v32, v32, v33
	v_mul_f32_e32 v59, 0x3e0293ee, v32
	v_pk_mul_f32 v[32:33], v[56:57], v[90:91]
	v_mov_b32_e32 v63, v181
	v_add_f32_e32 v32, v32, v33
	v_mul_f32_e32 v56, 0x3e0293ee, v32
	v_pk_mul_f32 v[32:33], v[54:55], v[92:93] op_sel:[1,0] op_sel_hi:[0,1]
	v_sub_f32_e32 v32, v32, v33
	v_mul_f32_e32 v57, 0x3e0293ee, v32
	v_pk_mul_f32 v[32:33], v[54:55], v[92:93]
	v_cvt_pk_bf16_f32 v152, v59, v57
	v_mov_b32_e32 v57, v181
	v_add_f32_e32 v32, v32, v33
	v_mul_f32_e32 v54, 0x3e0293ee, v32
	v_pk_mul_f32 v[32:33], v[52:53], v[86:87] op_sel:[1,0] op_sel_hi:[0,1]
	v_sub_f32_e32 v32, v32, v33
	v_mul_f32_e32 v55, 0x3e0293ee, v32
	v_pk_mul_f32 v[32:33], v[52:53], v[86:87]
	v_mov_b32_e32 v59, v181
	v_add_f32_e32 v32, v32, v33
	v_mul_f32_e32 v52, 0x3e0293ee, v32
	v_pk_mul_f32 v[32:33], v[50:51], v[88:89] op_sel:[1,0] op_sel_hi:[0,1]
	v_sub_f32_e32 v32, v32, v33
	v_mul_f32_e32 v53, 0x3e0293ee, v32
	v_pk_mul_f32 v[32:33], v[50:51], v[88:89]
	v_cvt_pk_bf16_f32 v153, v55, v53
	v_mov_b32_e32 v71, v181
	v_add_f32_e32 v32, v32, v33
	v_mul_f32_e32 v50, 0x3e0293ee, v32
	s_waitcnt vmcnt(0)
	v_pk_mul_f32 v[32:33], v[48:49], v[40:41] op_sel:[1,0] op_sel_hi:[0,1]
	v_sub_f32_e32 v32, v32, v33
	v_mul_f32_e32 v51, 0x3e0293ee, v32
	v_pk_mul_f32 v[32:33], v[48:49], v[40:41]
	v_mov_b32_e32 v72, v181
	v_add_f32_e32 v32, v32, v33
	v_mul_f32_e32 v40, 0x3e0293ee, v32
	v_pk_mul_f32 v[32:33], v[46:47], v[42:43] op_sel:[1,0] op_sel_hi:[0,1]
	v_sub_f32_e32 v32, v32, v33
	v_mul_f32_e32 v41, 0x3e0293ee, v32
	v_pk_mul_f32 v[32:33], v[46:47], v[42:43]
	v_cvt_pk_bf16_f32 v154, v51, v41
	v_mov_b32_e32 v73, v181
	v_add_f32_e32 v32, v32, v33
	v_mul_f32_e32 v42, 0x3e0293ee, v32
	v_pk_mul_f32 v[32:33], v[44:45], v[36:37] op_sel:[1,0] op_sel_hi:[0,1]
	v_sub_f32_e32 v32, v32, v33
	v_mul_f32_e32 v43, 0x3e0293ee, v32
	v_pk_mul_f32 v[32:33], v[44:45], v[36:37]
	v_mov_b32_e32 v75, v181
	v_add_f32_e32 v32, v32, v33
	v_mul_f32_e32 v36, 0x3e0293ee, v32
	v_pk_mul_f32 v[32:33], v[34:35], v[38:39] op_sel:[1,0] op_sel_hi:[0,1]
	v_sub_f32_e32 v32, v32, v33
	v_mul_f32_e32 v37, 0x3e0293ee, v32
	v_pk_mul_f32 v[32:33], v[34:35], v[38:39]
	v_cvt_pk_bf16_f32 v155, v43, v37
	v_cvt_pk_bf16_f32 v148, v76, v74
	v_cvt_pk_bf16_f32 v149, v64, v66
	v_cvt_pk_bf16_f32 v150, v68, v62
	v_cvt_pk_bf16_f32 v151, v60, v58
	s_nop 0
	v_add_f32_e32 v32, v32, v33
	v_mul_f32_e32 v32, 0x3e0293ee, v32
	v_cvt_pk_bf16_f32 v144, v56, v54
	v_cvt_pk_bf16_f32 v145, v52, v50
	v_cvt_pk_bf16_f32 v146, v40, v42
	v_cvt_pk_bf16_f32 v147, v36, v32
	v_and_or_b32 v32, s8, 32, v202
	s_lshr_b32 s0, s97, 3
	s_and_b32 s0, s0, 0x1ffffff0
	v_mov_b32_e32 v33, s0
	v_mad_u32_u24 v32, v32, s82, v33
	v_or_b32_e32 v32, v32, v203
	v_lshlrev_b32_e32 v180, 1, v32
	s_lshr_b32 s0, s97, 4
	s_and_b32 s5, s0, 0xffffff0
	s_lshr_b32 s0, s97, 5
	v_and_or_b32 v32, s0, 2, v179
	s_lshr_b32 s18, s97, 4
	s_and_b32 s18, s18, 8
	v_bfe_u32 v33, v177, 2, 3
	v_or_b32_e32 v33, s5, v33
	v_or_b32_e32 v33, s18, v33
	v_lshlrev_b32_e32 v32, 5, v32
	v_mul_lo_u32 v33, v33, s82
	v_or3_b32 v32, v32, v204, v33
	v_lshlrev_b32_e32 v199, 1, v32
	v_add_u32_e32 v198, 0x80, v180
	v_add_u32_e32 v219, 0x48000, v199
	s_lshl_b32 s0, s33, 10
	s_add_i32 s74, s0, 16
	s_add_i32 s68, s0, 0x10010
	s_add_i32 m0, s74, 0
	s_nop 0
	global_load_lds_dwordx4 v180, s[72:73]
	s_add_i32 m0, s74, 8192
	s_nop 0
	global_load_lds_dwordx4 v198, s[72:73]
	s_add_u32 s72, s72, 0x90000
	s_addc_u32 s73, s73, 0
	s_add_i32 m0, s74, 16384
	s_nop 0
	global_load_lds_dwordx4 v180, s[72:73]
	s_add_i32 m0, s74, 24576
	s_nop 0
	global_load_lds_dwordx4 v198, s[72:73]
	s_add_u32 s72, s72, 0x90000
	s_addc_u32 s73, s73, 0
	s_add_i32 m0, s68, 0
	s_nop 0
	global_load_lds_dwordx4 v199, s[70:71]
	s_add_i32 m0, s68, 8192
	s_nop 0
	global_load_lds_dwordx4 v219, s[70:71]
	s_add_u32 s70, s70, 0x90000
	s_addc_u32 s71, s71, 0
	s_add_i32 m0, s74, 32768
	s_nop 0
	global_load_lds_dwordx4 v180, s[72:73]
	s_add_i32 m0, s74, 40960
	s_nop 0
	global_load_lds_dwordx4 v198, s[72:73]
	s_add_u32 s72, s72, 0x90000
	s_addc_u32 s73, s73, 0
	s_add_i32 m0, s68, 16384
	s_nop 0
	global_load_lds_dwordx4 v199, s[70:71]
	s_add_i32 m0, s68, 24576
	s_nop 0
	global_load_lds_dwordx4 v219, s[70:71]
	s_add_u32 s70, s70, 0x90000
	s_addc_u32 s71, s71, 0
	s_add_i32 m0, s74, 49152
	s_nop 0
	global_load_lds_dwordx4 v180, s[72:73]
	s_add_i32 m0, s74, 57344
	s_nop 0
	global_load_lds_dwordx4 v198, s[72:73]
	s_add_u32 s72, s72, 0x90000
	s_addc_u32 s73, s73, 0
	s_add_i32 m0, s68, 32768
	s_nop 0
	global_load_lds_dwordx4 v199, s[70:71]
	s_add_i32 m0, s68, 40960
	s_nop 0
	global_load_lds_dwordx4 v219, s[70:71]
	s_add_u32 s70, s70, 0x90000
	s_addc_u32 s71, s71, 0
	v_mov_b32_e32 v80, 0
	v_mov_b32_e32 v81, 0
	v_mov_b32_e32 v82, 0
	v_mov_b32_e32 v83, 0
	v_mov_b32_e32 v84, 0
	v_mov_b32_e32 v85, 0
	v_mov_b32_e32 v86, 0
	v_mov_b32_e32 v87, 0
	v_mov_b32_e32 v88, 0
	v_mov_b32_e32 v89, 0
	v_mov_b32_e32 v90, 0
	v_mov_b32_e32 v91, 0
	v_mov_b32_e32 v92, 0
	v_mov_b32_e32 v93, 0
	v_mov_b32_e32 v94, 0
	v_mov_b32_e32 v95, 0
	v_mov_b32_e32 v64, 0
	v_mov_b32_e32 v65, 0
	v_mov_b32_e32 v66, 0
	v_mov_b32_e32 v67, 0
	v_mov_b32_e32 v68, 0
	v_mov_b32_e32 v69, 0
	v_mov_b32_e32 v70, 0
	v_mov_b32_e32 v71, 0
	v_mov_b32_e32 v72, 0
	v_mov_b32_e32 v73, 0
	v_mov_b32_e32 v74, 0
	v_mov_b32_e32 v75, 0
	v_mov_b32_e32 v76, 0
	v_mov_b32_e32 v77, 0
	v_mov_b32_e32 v78, 0
	v_mov_b32_e32 v79, 0
	v_mov_b32_e32 v48, 0
	v_mov_b32_e32 v49, 0
	v_mov_b32_e32 v50, 0
	v_mov_b32_e32 v51, 0
	v_mov_b32_e32 v52, 0
	v_mov_b32_e32 v53, 0
	v_mov_b32_e32 v54, 0
	v_mov_b32_e32 v55, 0
	v_mov_b32_e32 v56, 0
	v_mov_b32_e32 v57, 0
	v_mov_b32_e32 v58, 0
	v_mov_b32_e32 v59, 0
	v_mov_b32_e32 v60, 0
	v_mov_b32_e32 v61, 0
	v_mov_b32_e32 v62, 0
	v_mov_b32_e32 v63, 0
	v_mov_b32_e32 v32, 0
	v_mov_b32_e32 v33, 0
	v_mov_b32_e32 v34, 0
	v_mov_b32_e32 v35, 0
	v_mov_b32_e32 v36, 0
	v_mov_b32_e32 v37, 0
	v_mov_b32_e32 v38, 0
	v_mov_b32_e32 v39, 0
	v_mov_b32_e32 v40, 0
	v_mov_b32_e32 v41, 0
	v_mov_b32_e32 v42, 0
	v_mov_b32_e32 v43, 0
	v_mov_b32_e32 v44, 0
	v_mov_b32_e32 v45, 0
	v_mov_b32_e32 v46, 0
	v_mov_b32_e32 v47, 0
	v_mov_b32_e32 v218, 0
	v_mov_b32_e32 v248, 0
	v_mov_b32_e32 v249, 0
	v_mov_b32_e32 v251, 0
	s_waitcnt vmcnt(8)
	s_barrier
	ds_read_b128 v[236:239], v206 offset:0
	ds_read_b128 v[240:243], v206 offset:2048
	ds_read_b128 v[244:247], v206 offset:4096
	s_waitcnt lgkmcnt(2)
	v_mfma_f32_32x32x16_bf16 v[96:111], v[236:239], v[172:175], v[16:31]
	ds_read_b128 v[190:193], v206 offset:6144
	s_waitcnt lgkmcnt(2)
	v_mfma_f32_32x32x16_bf16 v[96:111], v[240:243], v[168:171], v[96:111]
	ds_read_b128 v[194:197], v206 offset:8192
	s_waitcnt lgkmcnt(2)
	v_mfma_f32_32x32x16_bf16 v[96:111], v[244:247], v[164:167], v[96:111]
	ds_read_b128 v[252:255], v206 offset:10240
	s_waitcnt lgkmcnt(2)
	v_mfma_f32_32x32x16_bf16 v[96:111], v[190:193], v[160:163], v[96:111]
	ds_read_b128 v[236:239], v206 offset:12288
	s_waitcnt lgkmcnt(2)
	v_mfma_f32_32x32x16_bf16 v[96:111], v[194:197], v[156:159], v[96:111]
	ds_read_b128 v[240:243], v206 offset:14336
	s_waitcnt lgkmcnt(2)
	v_mfma_f32_32x32x16_bf16 v[96:111], v[252:255], v[152:155], v[96:111]
	ds_read_b128 v[244:247], v206 offset:1024
	s_waitcnt lgkmcnt(2)
	v_mfma_f32_32x32x16_bf16 v[96:111], v[236:239], v[148:151], v[96:111]
	ds_read_b128 v[190:193], v206 offset:3072
	s_waitcnt lgkmcnt(2)
	v_mfma_f32_32x32x16_bf16 v[96:111], v[240:243], v[144:147], v[96:111]
	ds_read_b128 v[194:197], v206 offset:5120
	s_waitcnt lgkmcnt(2)
	v_mfma_f32_32x32x16_bf16 v[112:127], v[244:247], v[172:175], v[16:31]
	ds_read_b128 v[252:255], v206 offset:7168
	s_waitcnt lgkmcnt(2)
	v_mfma_f32_32x32x16_bf16 v[112:127], v[190:193], v[168:171], v[112:127]
	ds_read_b128 v[236:239], v206 offset:9216
	s_waitcnt lgkmcnt(2)
	v_mfma_f32_32x32x16_bf16 v[112:127], v[194:197], v[164:167], v[112:127]
	ds_read_b128 v[240:243], v206 offset:11264
	s_waitcnt lgkmcnt(2)
	v_mfma_f32_32x32x16_bf16 v[112:127], v[252:255], v[160:163], v[112:127]
	ds_read_b128 v[244:247], v206 offset:13312
	s_waitcnt lgkmcnt(2)
	v_mfma_f32_32x32x16_bf16 v[112:127], v[236:239], v[156:159], v[112:127]
	ds_read_b128 v[190:193], v206 offset:15360
	s_waitcnt lgkmcnt(2)
	v_mfma_f32_32x32x16_bf16 v[112:127], v[240:243], v[152:155], v[112:127]
	s_waitcnt lgkmcnt(1)
	v_mfma_f32_32x32x16_bf16 v[112:127], v[244:247], v[148:151], v[112:127]
	s_waitcnt lgkmcnt(0)
	v_mfma_f32_32x32x16_bf16 v[112:127], v[190:193], v[144:147], v[112:127]
	ds_read_b128 v[236:239], v206 offset:16384
	ds_read_b128 v[240:243], v206 offset:18432
	ds_read_b128 v[244:247], v206 offset:20480
	v_exp_f32_e32 v96, v96
	v_exp_f32_e32 v97, v97
	v_exp_f32_e32 v98, v98
	v_exp_f32_e32 v99, v99
	v_exp_f32_e32 v100, v100
	v_exp_f32_e32 v101, v101
	v_exp_f32_e32 v102, v102
	v_exp_f32_e32 v103, v103
	v_exp_f32_e32 v104, v104
	v_exp_f32_e32 v105, v105
	v_exp_f32_e32 v106, v106
	v_exp_f32_e32 v107, v107
	v_exp_f32_e32 v108, v108
	v_exp_f32_e32 v109, v109
	v_exp_f32_e32 v110, v110
	v_exp_f32_e32 v111, v111
	v_exp_f32_e32 v112, v112
	v_exp_f32_e32 v113, v113
	v_exp_f32_e32 v114, v114
	v_exp_f32_e32 v115, v115
	v_exp_f32_e32 v116, v116
	v_exp_f32_e32 v117, v117
	v_exp_f32_e32 v118, v118
	v_exp_f32_e32 v119, v119
	v_exp_f32_e32 v120, v120
	v_exp_f32_e32 v121, v121
	v_exp_f32_e32 v122, v122
	v_exp_f32_e32 v123, v123
	v_exp_f32_e32 v124, v124
	v_exp_f32_e32 v125, v125
	v_exp_f32_e32 v126, v126
	v_exp_f32_e32 v127, v127
	s_movk_i32 s98, 63
.Lattn_loop:
	s_waitcnt lgkmcnt(2)
	v_mfma_f32_32x32x16_bf16 v[128:143], v[236:239], v[172:175], v[16:31]
	ds_read_b128 v[190:193], v206 offset:22528
	s_add_i32 m0, s74, 0
	v_cvt_pk_bf16_f32 v220, v96, v97
	v_cvt_pk_bf16_f32 v221, v98, v99
	v_cvt_pk_bf16_f32 v222, v100, v101
	global_load_lds_dwordx4 v180, s[72:73]
	s_waitcnt lgkmcnt(2)
	v_mfma_f32_32x32x16_bf16 v[128:143], v[240:243], v[168:171], v[128:143]
	ds_read_b128 v[194:197], v206 offset:24576
	s_add_i32 m0, s74, 8192
	v_cvt_pk_bf16_f32 v223, v102, v103
	v_add_f32_e32 v218, v96, v218
	v_add_f32_e32 v248, v97, v248
	global_load_lds_dwordx4 v198, s[72:73]
	s_add_u32 s72, s72, 0x90000
	s_addc_u32 s73, s73, 0
	s_waitcnt lgkmcnt(2)
	v_mfma_f32_32x32x16_bf16 v[128:143], v[244:247], v[164:167], v[128:143]
	ds_read_b128 v[252:255], v206 offset:26624
	s_add_i32 m0, s68, 49152
	v_add_f32_e32 v218, v98, v218
	v_add_f32_e32 v248, v99, v248
	v_add_f32_e32 v218, v100, v218
	global_load_lds_dwordx4 v199, s[70:71]
	s_waitcnt lgkmcnt(2)
	v_mfma_f32_32x32x16_bf16 v[128:143], v[190:193], v[160:163], v[128:143]
	ds_read_b128 v[236:239], v206 offset:28672
	s_add_i32 m0, s68, 57344
	v_add_f32_e32 v248, v101, v248
	v_add_f32_e32 v218, v102, v218
	v_add_f32_e32 v248, v103, v248
	global_load_lds_dwordx4 v219, s[70:71]
	s_add_u32 s70, s70, 0x90000
	s_addc_u32 s71, s71, 0
	s_waitcnt lgkmcnt(2)
	v_mfma_f32_32x32x16_bf16 v[128:143], v[194:197], v[156:159], v[128:143]
	ds_read_b128 v[240:243], v206 offset:30720
	v_cvt_pk_bf16_f32 v224, v104, v105
	v_cvt_pk_bf16_f32 v225, v106, v107
	v_cvt_pk_bf16_f32 v226, v108, v109
	s_waitcnt lgkmcnt(2)
	v_mfma_f32_32x32x16_bf16 v[128:143], v[252:255], v[152:155], v[128:143]
	ds_read_b128 v[244:247], v206 offset:17408
	v_cvt_pk_bf16_f32 v227, v110, v111
	v_add_f32_e32 v218, v104, v218
	v_add_f32_e32 v248, v105, v248
	s_waitcnt lgkmcnt(2)
	v_mfma_f32_32x32x16_bf16 v[128:143], v[236:239], v[148:151], v[128:143]
	ds_read_b128 v[190:193], v206 offset:19456
	v_add_f32_e32 v218, v106, v218
	v_add_f32_e32 v248, v107, v248
	v_add_f32_e32 v218, v108, v218
	s_waitcnt lgkmcnt(2)
	v_mfma_f32_32x32x16_bf16 v[128:143], v[240:243], v[144:147], v[128:143]
	ds_read_b128 v[194:197], v206 offset:21504
	v_add_f32_e32 v248, v109, v248
	v_add_f32_e32 v218, v110, v218
	v_add_f32_e32 v248, v111, v248
	s_waitcnt lgkmcnt(2)
	v_mfma_f32_32x32x16_bf16 v[0:15], v[244:247], v[172:175], v[16:31]
	ds_read_b128 v[252:255], v206 offset:23552
	v_cvt_pk_bf16_f32 v228, v112, v113
	v_cvt_pk_bf16_f32 v229, v114, v115
	v_cvt_pk_bf16_f32 v230, v116, v117
	s_waitcnt lgkmcnt(2)
	v_mfma_f32_32x32x16_bf16 v[0:15], v[190:193], v[168:171], v[0:15]
	ds_read_b128 v[236:239], v206 offset:25600
	v_cvt_pk_bf16_f32 v231, v118, v119
	v_add_f32_e32 v249, v112, v249
	v_add_f32_e32 v251, v113, v251
	s_waitcnt lgkmcnt(2)
	v_mfma_f32_32x32x16_bf16 v[0:15], v[194:197], v[164:167], v[0:15]
	ds_read_b128 v[240:243], v206 offset:27648
	v_add_f32_e32 v249, v114, v249
	v_add_f32_e32 v251, v115, v251
	v_add_f32_e32 v249, v116, v249
	s_waitcnt lgkmcnt(2)
	v_mfma_f32_32x32x16_bf16 v[0:15], v[252:255], v[160:163], v[0:15]
	ds_read_b128 v[244:247], v206 offset:29696
	v_add_f32_e32 v251, v117, v251
	v_add_f32_e32 v249, v118, v249
	v_add_f32_e32 v251, v119, v251
	s_waitcnt lgkmcnt(2)
	v_mfma_f32_32x32x16_bf16 v[0:15], v[236:239], v[156:159], v[0:15]
	ds_read_b128 v[190:193], v206 offset:31744
	v_cvt_pk_bf16_f32 v232, v120, v121
	v_cvt_pk_bf16_f32 v233, v122, v123
	v_cvt_pk_bf16_f32 v234, v124, v125
	s_waitcnt lgkmcnt(2)
	v_mfma_f32_32x32x16_bf16 v[0:15], v[240:243], v[152:155], v[0:15]
	ds_read_b64_tr_b16 v[194:195], v201 offset:0
	ds_read_b64_tr_b16 v[196:197], v201 offset:2048
	v_cvt_pk_bf16_f32 v235, v126, v127
	v_add_f32_e32 v249, v120, v249
	v_add_f32_e32 v251, v121, v251
	s_waitcnt lgkmcnt(3)
	v_mfma_f32_32x32x16_bf16 v[0:15], v[244:247], v[148:151], v[0:15]
	ds_read_b64_tr_b16 v[252:253], v201 offset:4096
	ds_read_b64_tr_b16 v[254:255], v201 offset:6144
	v_add_f32_e32 v249, v122, v249
	v_add_f32_e32 v251, v123, v251
	v_add_f32_e32 v249, v124, v249
	s_waitcnt lgkmcnt(4)
	v_mfma_f32_32x32x16_bf16 v[0:15], v[190:193], v[144:147], v[0:15]
	ds_read_b64_tr_b16 v[236:237], v201 offset:8192
	ds_read_b64_tr_b16 v[238:239], v201 offset:10240
	v_add_f32_e32 v251, v125, v251
	v_add_f32_e32 v249, v126, v249
	v_add_f32_e32 v251, v127, v251
	s_waitcnt lgkmcnt(4)
	v_mfma_f32_32x32x16_bf16 v[80:95], v[220:223], v[194:197], v[80:95]
	ds_read_b64_tr_b16 v[240:241], v201 offset:12288
	ds_read_b64_tr_b16 v[242:243], v201 offset:14336
	v_exp_f32_e32 v128, v128
	v_exp_f32_e32 v129, v129
	s_waitcnt lgkmcnt(4)
	v_mfma_f32_32x32x16_bf16 v[80:95], v[224:227], v[252:255], v[80:95]
	ds_read_b64_tr_b16 v[244:245], v201 offset:512
	ds_read_b64_tr_b16 v[246:247], v201 offset:2560
	v_exp_f32_e32 v130, v130
	v_exp_f32_e32 v131, v131
	s_waitcnt lgkmcnt(4)
	v_mfma_f32_32x32x16_bf16 v[80:95], v[228:231], v[236:239], v[80:95]
	ds_read_b64_tr_b16 v[190:191], v201 offset:4608
	ds_read_b64_tr_b16 v[192:193], v201 offset:6656
	v_exp_f32_e32 v132, v132
	v_exp_f32_e32 v133, v133
	s_waitcnt lgkmcnt(4)
	v_mfma_f32_32x32x16_bf16 v[80:95], v[232:235], v[240:243], v[80:95]
	ds_read_b64_tr_b16 v[194:195], v201 offset:8704
	ds_read_b64_tr_b16 v[196:197], v201 offset:10752
	v_exp_f32_e32 v134, v134
	v_exp_f32_e32 v135, v135
	s_waitcnt lgkmcnt(4)
	v_mfma_f32_32x32x16_bf16 v[64:79], v[220:223], v[244:247], v[64:79]
	ds_read_b64_tr_b16 v[252:253], v201 offset:12800
	ds_read_b64_tr_b16 v[254:255], v201 offset:14848
	v_exp_f32_e32 v136, v136
	v_exp_f32_e32 v137, v137
	s_waitcnt lgkmcnt(4)
	v_mfma_f32_32x32x16_bf16 v[64:79], v[224:227], v[190:193], v[64:79]
	ds_read_b64_tr_b16 v[236:237], v201 offset:1024
	ds_read_b64_tr_b16 v[238:239], v201 offset:3072
	v_exp_f32_e32 v138, v138
	v_exp_f32_e32 v139, v139
	s_waitcnt lgkmcnt(4)
	v_mfma_f32_32x32x16_bf16 v[64:79], v[228:231], v[194:197], v[64:79]
	ds_read_b64_tr_b16 v[240:241], v201 offset:5120
	ds_read_b64_tr_b16 v[242:243], v201 offset:7168
	v_exp_f32_e32 v140, v140
	v_exp_f32_e32 v141, v141
	s_waitcnt lgkmcnt(4)
	v_mfma_f32_32x32x16_bf16 v[64:79], v[232:235], v[252:255], v[64:79]
	ds_read_b64_tr_b16 v[244:245], v201 offset:9216
	ds_read_b64_tr_b16 v[246:247], v201 offset:11264
	v_exp_f32_e32 v142, v142
	v_exp_f32_e32 v143, v143
	s_waitcnt lgkmcnt(4)
	v_mfma_f32_32x32x16_bf16 v[48:63], v[220:223], v[236:239], v[48:63]
	ds_read_b64_tr_b16 v[236:237], v201 offset:13312
	ds_read_b64_tr_b16 v[238:239], v201 offset:15360
	ds_read_b64_tr_b16 v[190:191], v201 offset:5632
	ds_read_b64_tr_b16 v[192:193], v201 offset:7680
	v_exp_f32_e32 v0, v0
	v_exp_f32_e32 v1, v1
	s_waitcnt lgkmcnt(6)
	v_mfma_f32_32x32x16_bf16 v[48:63], v[224:227], v[240:243], v[48:63]
	ds_read_b64_tr_b16 v[240:241], v201 offset:1536
	ds_read_b64_tr_b16 v[242:243], v201 offset:3584
	ds_read_b64_tr_b16 v[194:195], v201 offset:9728
	ds_read_b64_tr_b16 v[196:197], v201 offset:11776
	v_exp_f32_e32 v2, v2
	v_exp_f32_e32 v3, v3
	s_waitcnt lgkmcnt(8)
	v_mfma_f32_32x32x16_bf16 v[48:63], v[228:231], v[244:247], v[48:63]
	ds_read_b64_tr_b16 v[252:253], v201 offset:13824
	ds_read_b64_tr_b16 v[254:255], v201 offset:15872
	v_exp_f32_e32 v4, v4
	v_exp_f32_e32 v5, v5
	s_waitcnt lgkmcnt(8)
	v_mfma_f32_32x32x16_bf16 v[48:63], v[232:235], v[236:239], v[48:63]
	v_exp_f32_e32 v6, v6
	v_exp_f32_e32 v7, v7
	s_waitcnt lgkmcnt(4)
	v_mfma_f32_32x32x16_bf16 v[32:47], v[220:223], v[240:243], v[32:47]
	v_exp_f32_e32 v8, v8
	v_exp_f32_e32 v9, v9
	s_waitcnt vmcnt(8) lgkmcnt(0)
	s_barrier
	ds_read_b128 v[236:239], v206 offset:32768
	ds_read_b128 v[240:243], v206 offset:34816
	ds_read_b128 v[244:247], v206 offset:36864
	v_mfma_f32_32x32x16_bf16 v[32:47], v[224:227], v[190:193], v[32:47]
	v_exp_f32_e32 v10, v10
	v_exp_f32_e32 v11, v11
	v_mfma_f32_32x32x16_bf16 v[32:47], v[228:231], v[194:197], v[32:47]
	v_exp_f32_e32 v12, v12
	v_exp_f32_e32 v13, v13
	v_mfma_f32_32x32x16_bf16 v[32:47], v[232:235], v[252:255], v[32:47]
	v_exp_f32_e32 v14, v14
	v_exp_f32_e32 v15, v15
	s_waitcnt lgkmcnt(2)
	v_mfma_f32_32x32x16_bf16 v[96:111], v[236:239], v[172:175], v[16:31]
	ds_read_b128 v[190:193], v206 offset:38912
	s_add_i32 m0, s74, 16384
	v_cvt_pk_bf16_f32 v220, v128, v129
	v_cvt_pk_bf16_f32 v221, v130, v131
	v_cvt_pk_bf16_f32 v222, v132, v133
	global_load_lds_dwordx4 v180, s[72:73]
	s_waitcnt lgkmcnt(2)
	v_mfma_f32_32x32x16_bf16 v[96:111], v[240:243], v[168:171], v[96:111]
	ds_read_b128 v[194:197], v206 offset:40960
	s_add_i32 m0, s74, 24576
	v_cvt_pk_bf16_f32 v223, v134, v135
	v_add_f32_e32 v218, v128, v218
	v_add_f32_e32 v248, v129, v248
	global_load_lds_dwordx4 v198, s[72:73]
	s_add_u32 s72, s72, 0x90000
	s_addc_u32 s73, s73, 0
	s_waitcnt lgkmcnt(2)
	v_mfma_f32_32x32x16_bf16 v[96:111], v[244:247], v[164:167], v[96:111]
	ds_read_b128 v[252:255], v206 offset:43008
	s_add_i32 m0, s68, 0
	v_add_f32_e32 v218, v130, v218
	v_add_f32_e32 v248, v131, v248
	v_add_f32_e32 v218, v132, v218
	global_load_lds_dwordx4 v199, s[70:71]
	s_waitcnt lgkmcnt(2)
	v_mfma_f32_32x32x16_bf16 v[96:111], v[190:193], v[160:163], v[96:111]
	ds_read_b128 v[236:239], v206 offset:45056
	s_add_i32 m0, s68, 8192
	v_add_f32_e32 v248, v133, v248
	v_add_f32_e32 v218, v134, v218
	v_add_f32_e32 v248, v135, v248
	global_load_lds_dwordx4 v219, s[70:71]
	s_add_u32 s70, s70, 0x90000
	s_addc_u32 s71, s71, 0
	s_waitcnt lgkmcnt(2)
	v_mfma_f32_32x32x16_bf16 v[96:111], v[194:197], v[156:159], v[96:111]
	ds_read_b128 v[240:243], v206 offset:47104
	v_cvt_pk_bf16_f32 v224, v136, v137
	v_cvt_pk_bf16_f32 v225, v138, v139
	v_cvt_pk_bf16_f32 v226, v140, v141
	s_waitcnt lgkmcnt(2)
	v_mfma_f32_32x32x16_bf16 v[96:111], v[252:255], v[152:155], v[96:111]
	ds_read_b128 v[244:247], v206 offset:33792
	v_cvt_pk_bf16_f32 v227, v142, v143
	v_add_f32_e32 v218, v136, v218
	v_add_f32_e32 v248, v137, v248
	s_waitcnt lgkmcnt(2)
	v_mfma_f32_32x32x16_bf16 v[96:111], v[236:239], v[148:151], v[96:111]
	ds_read_b128 v[190:193], v206 offset:35840
	v_add_f32_e32 v218, v138, v218
	v_add_f32_e32 v248, v139, v248
	v_add_f32_e32 v218, v140, v218
	s_waitcnt lgkmcnt(2)
	v_mfma_f32_32x32x16_bf16 v[96:111], v[240:243], v[144:147], v[96:111]
	ds_read_b128 v[194:197], v206 offset:37888
	v_add_f32_e32 v248, v141, v248
	v_add_f32_e32 v218, v142, v218
	v_add_f32_e32 v248, v143, v248
	s_waitcnt lgkmcnt(2)
	v_mfma_f32_32x32x16_bf16 v[112:127], v[244:247], v[172:175], v[16:31]
	ds_read_b128 v[252:255], v206 offset:39936
	v_cvt_pk_bf16_f32 v228, v0, v1
	v_cvt_pk_bf16_f32 v229, v2, v3
	v_cvt_pk_bf16_f32 v230, v4, v5
	s_waitcnt lgkmcnt(2)
	v_mfma_f32_32x32x16_bf16 v[112:127], v[190:193], v[168:171], v[112:127]
	ds_read_b128 v[236:239], v206 offset:41984
	v_cvt_pk_bf16_f32 v231, v6, v7
	v_add_f32_e32 v249, v0, v249
	v_add_f32_e32 v251, v1, v251
	s_waitcnt lgkmcnt(2)
	v_mfma_f32_32x32x16_bf16 v[112:127], v[194:197], v[164:167], v[112:127]
	ds_read_b128 v[240:243], v206 offset:44032
	v_add_f32_e32 v249, v2, v249
	v_add_f32_e32 v251, v3, v251
	v_add_f32_e32 v249, v4, v249
	s_waitcnt lgkmcnt(2)
	v_mfma_f32_32x32x16_bf16 v[112:127], v[252:255], v[160:163], v[112:127]
	ds_read_b128 v[244:247], v206 offset:46080
	v_add_f32_e32 v251, v5, v251
	v_add_f32_e32 v249, v6, v249
	v_add_f32_e32 v251, v7, v251
	s_waitcnt lgkmcnt(2)
	v_mfma_f32_32x32x16_bf16 v[112:127], v[236:239], v[156:159], v[112:127]
	ds_read_b128 v[190:193], v206 offset:48128
	v_cvt_pk_bf16_f32 v232, v8, v9
	v_cvt_pk_bf16_f32 v233, v10, v11
	v_cvt_pk_bf16_f32 v234, v12, v13
	s_waitcnt lgkmcnt(2)
	v_mfma_f32_32x32x16_bf16 v[112:127], v[240:243], v[152:155], v[112:127]
	ds_read_b64_tr_b16 v[194:195], v201 offset:16384
	ds_read_b64_tr_b16 v[196:197], v201 offset:18432
	v_cvt_pk_bf16_f32 v235, v14, v15
	v_add_f32_e32 v249, v8, v249
	v_add_f32_e32 v251, v9, v251
	s_waitcnt lgkmcnt(3)
	v_mfma_f32_32x32x16_bf16 v[112:127], v[244:247], v[148:151], v[112:127]
	ds_read_b64_tr_b16 v[252:253], v201 offset:20480
	ds_read_b64_tr_b16 v[254:255], v201 offset:22528
	v_add_f32_e32 v249, v10, v249
	v_add_f32_e32 v251, v11, v251
	v_add_f32_e32 v249, v12, v249
	s_waitcnt lgkmcnt(4)
	v_mfma_f32_32x32x16_bf16 v[112:127], v[190:193], v[144:147], v[112:127]
	ds_read_b64_tr_b16 v[236:237], v201 offset:24576
	ds_read_b64_tr_b16 v[238:239], v201 offset:26624
	v_add_f32_e32 v251, v13, v251
	v_add_f32_e32 v249, v14, v249
	v_add_f32_e32 v251, v15, v251
	s_waitcnt lgkmcnt(4)
	v_mfma_f32_32x32x16_bf16 v[80:95], v[220:223], v[194:197], v[80:95]
	ds_read_b64_tr_b16 v[240:241], v201 offset:28672
	ds_read_b64_tr_b16 v[242:243], v201 offset:30720
	v_exp_f32_e32 v96, v96
	v_exp_f32_e32 v97, v97
	s_waitcnt lgkmcnt(4)
	v_mfma_f32_32x32x16_bf16 v[80:95], v[224:227], v[252:255], v[80:95]
	ds_read_b64_tr_b16 v[244:245], v201 offset:16896
	ds_read_b64_tr_b16 v[246:247], v201 offset:18944
	v_exp_f32_e32 v98, v98
	v_exp_f32_e32 v99, v99
	s_waitcnt lgkmcnt(4)
	v_mfma_f32_32x32x16_bf16 v[80:95], v[228:231], v[236:239], v[80:95]
	ds_read_b64_tr_b16 v[190:191], v201 offset:20992
	ds_read_b64_tr_b16 v[192:193], v201 offset:23040
	v_exp_f32_e32 v100, v100
	v_exp_f32_e32 v101, v101
	s_waitcnt lgkmcnt(4)
	v_mfma_f32_32x32x16_bf16 v[80:95], v[232:235], v[240:243], v[80:95]
	ds_read_b64_tr_b16 v[194:195], v201 offset:25088
	ds_read_b64_tr_b16 v[196:197], v201 offset:27136
	v_exp_f32_e32 v102, v102
	v_exp_f32_e32 v103, v103
	s_waitcnt lgkmcnt(4)
	v_mfma_f32_32x32x16_bf16 v[64:79], v[220:223], v[244:247], v[64:79]
	ds_read_b64_tr_b16 v[252:253], v201 offset:29184
	ds_read_b64_tr_b16 v[254:255], v201 offset:31232
	v_exp_f32_e32 v104, v104
	v_exp_f32_e32 v105, v105
	s_waitcnt lgkmcnt(4)
	v_mfma_f32_32x32x16_bf16 v[64:79], v[224:227], v[190:193], v[64:79]
	ds_read_b64_tr_b16 v[236:237], v201 offset:17408
	ds_read_b64_tr_b16 v[238:239], v201 offset:19456
	v_exp_f32_e32 v106, v106
	v_exp_f32_e32 v107, v107
	s_waitcnt lgkmcnt(4)
	v_mfma_f32_32x32x16_bf16 v[64:79], v[228:231], v[194:197], v[64:79]
	ds_read_b64_tr_b16 v[240:241], v201 offset:21504
	ds_read_b64_tr_b16 v[242:243], v201 offset:23552
	v_exp_f32_e32 v108, v108
	v_exp_f32_e32 v109, v109
	s_waitcnt lgkmcnt(4)
	v_mfma_f32_32x32x16_bf16 v[64:79], v[232:235], v[252:255], v[64:79]
	ds_read_b64_tr_b16 v[244:245], v201 offset:25600
	ds_read_b64_tr_b16 v[246:247], v201 offset:27648
	v_exp_f32_e32 v110, v110
	v_exp_f32_e32 v111, v111
	s_waitcnt lgkmcnt(4)
	v_mfma_f32_32x32x16_bf16 v[48:63], v[220:223], v[236:239], v[48:63]
	ds_read_b64_tr_b16 v[236:237], v201 offset:29696
	ds_read_b64_tr_b16 v[238:239], v201 offset:31744
	ds_read_b64_tr_b16 v[190:191], v201 offset:22016
	ds_read_b64_tr_b16 v[192:193], v201 offset:24064
	v_exp_f32_e32 v112, v112
	v_exp_f32_e32 v113, v113
	s_waitcnt lgkmcnt(6)
	v_mfma_f32_32x32x16_bf16 v[48:63], v[224:227], v[240:243], v[48:63]
	ds_read_b64_tr_b16 v[240:241], v201 offset:17920
	ds_read_b64_tr_b16 v[242:243], v201 offset:19968
	ds_read_b64_tr_b16 v[194:195], v201 offset:26112
	ds_read_b64_tr_b16 v[196:197], v201 offset:28160
	v_exp_f32_e32 v114, v114
	v_exp_f32_e32 v115, v115
	s_waitcnt lgkmcnt(8)
	v_mfma_f32_32x32x16_bf16 v[48:63], v[228:231], v[244:247], v[48:63]
	ds_read_b64_tr_b16 v[252:253], v201 offset:30208
	ds_read_b64_tr_b16 v[254:255], v201 offset:32256
	v_exp_f32_e32 v116, v116
	v_exp_f32_e32 v117, v117
	s_waitcnt lgkmcnt(8)
	v_mfma_f32_32x32x16_bf16 v[48:63], v[232:235], v[236:239], v[48:63]
	v_exp_f32_e32 v118, v118
	v_exp_f32_e32 v119, v119
	s_waitcnt lgkmcnt(4)
	v_mfma_f32_32x32x16_bf16 v[32:47], v[220:223], v[240:243], v[32:47]
	v_exp_f32_e32 v120, v120
	v_exp_f32_e32 v121, v121
	s_waitcnt vmcnt(8) lgkmcnt(0)
	s_barrier
	ds_read_b128 v[236:239], v206 offset:49152
	ds_read_b128 v[240:243], v206 offset:51200
	ds_read_b128 v[244:247], v206 offset:53248
	v_mfma_f32_32x32x16_bf16 v[32:47], v[224:227], v[190:193], v[32:47]
	v_exp_f32_e32 v122, v122
	v_exp_f32_e32 v123, v123
	v_mfma_f32_32x32x16_bf16 v[32:47], v[228:231], v[194:197], v[32:47]
	v_exp_f32_e32 v124, v124
	v_exp_f32_e32 v125, v125
	v_mfma_f32_32x32x16_bf16 v[32:47], v[232:235], v[252:255], v[32:47]
	v_exp_f32_e32 v126, v126
	v_exp_f32_e32 v127, v127
	s_waitcnt lgkmcnt(2)
	v_mfma_f32_32x32x16_bf16 v[128:143], v[236:239], v[172:175], v[16:31]
	ds_read_b128 v[190:193], v206 offset:55296
	s_add_i32 m0, s74, 32768
	v_cvt_pk_bf16_f32 v220, v96, v97
	v_cvt_pk_bf16_f32 v221, v98, v99
	v_cvt_pk_bf16_f32 v222, v100, v101
	global_load_lds_dwordx4 v180, s[72:73]
	s_waitcnt lgkmcnt(2)
	v_mfma_f32_32x32x16_bf16 v[128:143], v[240:243], v[168:171], v[128:143]
	ds_read_b128 v[194:197], v206 offset:57344
	s_add_i32 m0, s74, 40960
	v_cvt_pk_bf16_f32 v223, v102, v103
	v_add_f32_e32 v218, v96, v218
	v_add_f32_e32 v248, v97, v248
	global_load_lds_dwordx4 v198, s[72:73]
	s_add_u32 s72, s72, 0x90000
	s_addc_u32 s73, s73, 0
	s_waitcnt lgkmcnt(2)
	v_mfma_f32_32x32x16_bf16 v[128:143], v[244:247], v[164:167], v[128:143]
	ds_read_b128 v[252:255], v206 offset:59392
	s_add_i32 m0, s68, 16384
	v_add_f32_e32 v218, v98, v218
	v_add_f32_e32 v248, v99, v248
	v_add_f32_e32 v218, v100, v218
	global_load_lds_dwordx4 v199, s[70:71]
	s_waitcnt lgkmcnt(2)
	v_mfma_f32_32x32x16_bf16 v[128:143], v[190:193], v[160:163], v[128:143]
	ds_read_b128 v[236:239], v206 offset:61440
	s_add_i32 m0, s68, 24576
	v_add_f32_e32 v248, v101, v248
	v_add_f32_e32 v218, v102, v218
	v_add_f32_e32 v248, v103, v248
	global_load_lds_dwordx4 v219, s[70:71]
	s_add_u32 s70, s70, 0x90000
	s_addc_u32 s71, s71, 0
	s_waitcnt lgkmcnt(2)
	v_mfma_f32_32x32x16_bf16 v[128:143], v[194:197], v[156:159], v[128:143]
	ds_read_b128 v[240:243], v206 offset:63488
	v_cvt_pk_bf16_f32 v224, v104, v105
	v_cvt_pk_bf16_f32 v225, v106, v107
	v_cvt_pk_bf16_f32 v226, v108, v109
	s_waitcnt lgkmcnt(2)
	v_mfma_f32_32x32x16_bf16 v[128:143], v[252:255], v[152:155], v[128:143]
	ds_read_b128 v[244:247], v206 offset:50176
	v_cvt_pk_bf16_f32 v227, v110, v111
	v_add_f32_e32 v218, v104, v218
	v_add_f32_e32 v248, v105, v248
	s_waitcnt lgkmcnt(2)
	v_mfma_f32_32x32x16_bf16 v[128:143], v[236:239], v[148:151], v[128:143]
	ds_read_b128 v[190:193], v206 offset:52224
	v_add_f32_e32 v218, v106, v218
	v_add_f32_e32 v248, v107, v248
	v_add_f32_e32 v218, v108, v218
	s_waitcnt lgkmcnt(2)
	v_mfma_f32_32x32x16_bf16 v[128:143], v[240:243], v[144:147], v[128:143]
	ds_read_b128 v[194:197], v206 offset:54272
	v_add_f32_e32 v248, v109, v248
	v_add_f32_e32 v218, v110, v218
	v_add_f32_e32 v248, v111, v248
	s_waitcnt lgkmcnt(2)
	v_mfma_f32_32x32x16_bf16 v[0:15], v[244:247], v[172:175], v[16:31]
	ds_read_b128 v[252:255], v206 offset:56320
	v_cvt_pk_bf16_f32 v228, v112, v113
	v_cvt_pk_bf16_f32 v229, v114, v115
	v_cvt_pk_bf16_f32 v230, v116, v117
	s_waitcnt lgkmcnt(2)
	v_mfma_f32_32x32x16_bf16 v[0:15], v[190:193], v[168:171], v[0:15]
	ds_read_b128 v[236:239], v206 offset:58368
	v_cvt_pk_bf16_f32 v231, v118, v119
	v_add_f32_e32 v249, v112, v249
	v_add_f32_e32 v251, v113, v251
	s_waitcnt lgkmcnt(2)
	v_mfma_f32_32x32x16_bf16 v[0:15], v[194:197], v[164:167], v[0:15]
	ds_read_b128 v[240:243], v206 offset:60416
	v_add_f32_e32 v249, v114, v249
	v_add_f32_e32 v251, v115, v251
	v_add_f32_e32 v249, v116, v249
	s_waitcnt lgkmcnt(2)
	v_mfma_f32_32x32x16_bf16 v[0:15], v[252:255], v[160:163], v[0:15]
	ds_read_b128 v[244:247], v206 offset:62464
	v_add_f32_e32 v251, v117, v251
	v_add_f32_e32 v249, v118, v249
	v_add_f32_e32 v251, v119, v251
	s_waitcnt lgkmcnt(2)
	v_mfma_f32_32x32x16_bf16 v[0:15], v[236:239], v[156:159], v[0:15]
	ds_read_b128 v[190:193], v206 offset:64512
	v_cvt_pk_bf16_f32 v232, v120, v121
	v_cvt_pk_bf16_f32 v233, v122, v123
	v_cvt_pk_bf16_f32 v234, v124, v125
	s_waitcnt lgkmcnt(2)
	v_mfma_f32_32x32x16_bf16 v[0:15], v[240:243], v[152:155], v[0:15]
	ds_read_b64_tr_b16 v[194:195], v201 offset:32768
	ds_read_b64_tr_b16 v[196:197], v201 offset:34816
	v_cvt_pk_bf16_f32 v235, v126, v127
	v_add_f32_e32 v249, v120, v249
	v_add_f32_e32 v251, v121, v251
	s_waitcnt lgkmcnt(3)
	v_mfma_f32_32x32x16_bf16 v[0:15], v[244:247], v[148:151], v[0:15]
	ds_read_b64_tr_b16 v[252:253], v201 offset:36864
	ds_read_b64_tr_b16 v[254:255], v201 offset:38912
	v_add_f32_e32 v249, v122, v249
	v_add_f32_e32 v251, v123, v251
	v_add_f32_e32 v249, v124, v249
	s_waitcnt lgkmcnt(4)
	v_mfma_f32_32x32x16_bf16 v[0:15], v[190:193], v[144:147], v[0:15]
	ds_read_b64_tr_b16 v[236:237], v201 offset:40960
	ds_read_b64_tr_b16 v[238:239], v201 offset:43008
	v_add_f32_e32 v251, v125, v251
	v_add_f32_e32 v249, v126, v249
	v_add_f32_e32 v251, v127, v251
	s_waitcnt lgkmcnt(4)
	v_mfma_f32_32x32x16_bf16 v[80:95], v[220:223], v[194:197], v[80:95]
	ds_read_b64_tr_b16 v[240:241], v201 offset:45056
	ds_read_b64_tr_b16 v[242:243], v201 offset:47104
	v_exp_f32_e32 v128, v128
	v_exp_f32_e32 v129, v129
	s_waitcnt lgkmcnt(4)
	v_mfma_f32_32x32x16_bf16 v[80:95], v[224:227], v[252:255], v[80:95]
	ds_read_b64_tr_b16 v[244:245], v201 offset:33280
	ds_read_b64_tr_b16 v[246:247], v201 offset:35328
	v_exp_f32_e32 v130, v130
	v_exp_f32_e32 v131, v131
	s_waitcnt lgkmcnt(4)
	v_mfma_f32_32x32x16_bf16 v[80:95], v[228:231], v[236:239], v[80:95]
	ds_read_b64_tr_b16 v[190:191], v201 offset:37376
	ds_read_b64_tr_b16 v[192:193], v201 offset:39424
	v_exp_f32_e32 v132, v132
	v_exp_f32_e32 v133, v133
	s_waitcnt lgkmcnt(4)
	v_mfma_f32_32x32x16_bf16 v[80:95], v[232:235], v[240:243], v[80:95]
	ds_read_b64_tr_b16 v[194:195], v201 offset:41472
	ds_read_b64_tr_b16 v[196:197], v201 offset:43520
	v_exp_f32_e32 v134, v134
	v_exp_f32_e32 v135, v135
	s_waitcnt lgkmcnt(4)
	v_mfma_f32_32x32x16_bf16 v[64:79], v[220:223], v[244:247], v[64:79]
	ds_read_b64_tr_b16 v[252:253], v201 offset:45568
	ds_read_b64_tr_b16 v[254:255], v201 offset:47616
	v_exp_f32_e32 v136, v136
	v_exp_f32_e32 v137, v137
	s_waitcnt lgkmcnt(4)
	v_mfma_f32_32x32x16_bf16 v[64:79], v[224:227], v[190:193], v[64:79]
	ds_read_b64_tr_b16 v[236:237], v201 offset:33792
	ds_read_b64_tr_b16 v[238:239], v201 offset:35840
	v_exp_f32_e32 v138, v138
	v_exp_f32_e32 v139, v139
	s_waitcnt lgkmcnt(4)
	v_mfma_f32_32x32x16_bf16 v[64:79], v[228:231], v[194:197], v[64:79]
	ds_read_b64_tr_b16 v[240:241], v201 offset:37888
	ds_read_b64_tr_b16 v[242:243], v201 offset:39936
	v_exp_f32_e32 v140, v140
	v_exp_f32_e32 v141, v141
	s_waitcnt lgkmcnt(4)
	v_mfma_f32_32x32x16_bf16 v[64:79], v[232:235], v[252:255], v[64:79]
	ds_read_b64_tr_b16 v[244:245], v201 offset:41984
	ds_read_b64_tr_b16 v[246:247], v201 offset:44032
	v_exp_f32_e32 v142, v142
	v_exp_f32_e32 v143, v143
	s_waitcnt lgkmcnt(4)
	v_mfma_f32_32x32x16_bf16 v[48:63], v[220:223], v[236:239], v[48:63]
	ds_read_b64_tr_b16 v[236:237], v201 offset:46080
	ds_read_b64_tr_b16 v[238:239], v201 offset:48128
	ds_read_b64_tr_b16 v[190:191], v201 offset:38400
	ds_read_b64_tr_b16 v[192:193], v201 offset:40448
	v_exp_f32_e32 v0, v0
	v_exp_f32_e32 v1, v1
	s_waitcnt lgkmcnt(6)
	v_mfma_f32_32x32x16_bf16 v[48:63], v[224:227], v[240:243], v[48:63]
	ds_read_b64_tr_b16 v[240:241], v201 offset:34304
	ds_read_b64_tr_b16 v[242:243], v201 offset:36352
	ds_read_b64_tr_b16 v[194:195], v201 offset:42496
	ds_read_b64_tr_b16 v[196:197], v201 offset:44544
	v_exp_f32_e32 v2, v2
	v_exp_f32_e32 v3, v3
	s_waitcnt lgkmcnt(8)
	v_mfma_f32_32x32x16_bf16 v[48:63], v[228:231], v[244:247], v[48:63]
	ds_read_b64_tr_b16 v[252:253], v201 offset:46592
	ds_read_b64_tr_b16 v[254:255], v201 offset:48640
	v_exp_f32_e32 v4, v4
	v_exp_f32_e32 v5, v5
	s_waitcnt lgkmcnt(8)
	v_mfma_f32_32x32x16_bf16 v[48:63], v[232:235], v[236:239], v[48:63]
	v_exp_f32_e32 v6, v6
	v_exp_f32_e32 v7, v7
	s_waitcnt lgkmcnt(4)
	v_mfma_f32_32x32x16_bf16 v[32:47], v[220:223], v[240:243], v[32:47]
	v_exp_f32_e32 v8, v8
	v_exp_f32_e32 v9, v9
	s_waitcnt vmcnt(8) lgkmcnt(0)
	s_barrier
	ds_read_b128 v[236:239], v206 offset:0
	ds_read_b128 v[240:243], v206 offset:2048
	ds_read_b128 v[244:247], v206 offset:4096
	v_mfma_f32_32x32x16_bf16 v[32:47], v[224:227], v[190:193], v[32:47]
	v_exp_f32_e32 v10, v10
	v_exp_f32_e32 v11, v11
	v_mfma_f32_32x32x16_bf16 v[32:47], v[228:231], v[194:197], v[32:47]
	v_exp_f32_e32 v12, v12
	v_exp_f32_e32 v13, v13
	v_mfma_f32_32x32x16_bf16 v[32:47], v[232:235], v[252:255], v[32:47]
	v_exp_f32_e32 v14, v14
	v_exp_f32_e32 v15, v15
	s_waitcnt lgkmcnt(2)
	v_mfma_f32_32x32x16_bf16 v[96:111], v[236:239], v[172:175], v[16:31]
	ds_read_b128 v[190:193], v206 offset:6144
	s_add_i32 m0, s74, 49152
	v_cvt_pk_bf16_f32 v220, v128, v129
	v_cvt_pk_bf16_f32 v221, v130, v131
	v_cvt_pk_bf16_f32 v222, v132, v133
	global_load_lds_dwordx4 v180, s[72:73]
	s_waitcnt lgkmcnt(2)
	v_mfma_f32_32x32x16_bf16 v[96:111], v[240:243], v[168:171], v[96:111]
	ds_read_b128 v[194:197], v206 offset:8192
	s_add_i32 m0, s74, 57344
	v_cvt_pk_bf16_f32 v223, v134, v135
	v_add_f32_e32 v218, v128, v218
	v_add_f32_e32 v248, v129, v248
	global_load_lds_dwordx4 v198, s[72:73]
	s_add_u32 s72, s72, 0x90000
	s_addc_u32 s73, s73, 0
	s_waitcnt lgkmcnt(2)
	v_mfma_f32_32x32x16_bf16 v[96:111], v[244:247], v[164:167], v[96:111]
	ds_read_b128 v[252:255], v206 offset:10240
	s_add_i32 m0, s68, 32768
	v_add_f32_e32 v218, v130, v218
	v_add_f32_e32 v248, v131, v248
	v_add_f32_e32 v218, v132, v218
	global_load_lds_dwordx4 v199, s[70:71]
	s_waitcnt lgkmcnt(2)
	v_mfma_f32_32x32x16_bf16 v[96:111], v[190:193], v[160:163], v[96:111]
	ds_read_b128 v[236:239], v206 offset:12288
	s_add_i32 m0, s68, 40960
	v_add_f32_e32 v248, v133, v248
	v_add_f32_e32 v218, v134, v218
	v_add_f32_e32 v248, v135, v248
	global_load_lds_dwordx4 v219, s[70:71]
	s_add_u32 s70, s70, 0x90000
	s_addc_u32 s71, s71, 0
	s_waitcnt lgkmcnt(2)
	v_mfma_f32_32x32x16_bf16 v[96:111], v[194:197], v[156:159], v[96:111]
	ds_read_b128 v[240:243], v206 offset:14336
	v_cvt_pk_bf16_f32 v224, v136, v137
	v_cvt_pk_bf16_f32 v225, v138, v139
	v_cvt_pk_bf16_f32 v226, v140, v141
	s_waitcnt lgkmcnt(2)
	v_mfma_f32_32x32x16_bf16 v[96:111], v[252:255], v[152:155], v[96:111]
	ds_read_b128 v[244:247], v206 offset:1024
	v_cvt_pk_bf16_f32 v227, v142, v143
	v_add_f32_e32 v218, v136, v218
	v_add_f32_e32 v248, v137, v248
	s_waitcnt lgkmcnt(2)
	v_mfma_f32_32x32x16_bf16 v[96:111], v[236:239], v[148:151], v[96:111]
	ds_read_b128 v[190:193], v206 offset:3072
	v_add_f32_e32 v218, v138, v218
	v_add_f32_e32 v248, v139, v248
	v_add_f32_e32 v218, v140, v218
	s_waitcnt lgkmcnt(2)
	v_mfma_f32_32x32x16_bf16 v[96:111], v[240:243], v[144:147], v[96:111]
	ds_read_b128 v[194:197], v206 offset:5120
	v_add_f32_e32 v248, v141, v248
	v_add_f32_e32 v218, v142, v218
	v_add_f32_e32 v248, v143, v248
	s_waitcnt lgkmcnt(2)
	v_mfma_f32_32x32x16_bf16 v[112:127], v[244:247], v[172:175], v[16:31]
	ds_read_b128 v[252:255], v206 offset:7168
	v_cvt_pk_bf16_f32 v228, v0, v1
	v_cvt_pk_bf16_f32 v229, v2, v3
	v_cvt_pk_bf16_f32 v230, v4, v5
	s_waitcnt lgkmcnt(2)
	v_mfma_f32_32x32x16_bf16 v[112:127], v[190:193], v[168:171], v[112:127]
	ds_read_b128 v[236:239], v206 offset:9216
	v_cvt_pk_bf16_f32 v231, v6, v7
	v_add_f32_e32 v249, v0, v249
	v_add_f32_e32 v251, v1, v251
	s_waitcnt lgkmcnt(2)
	v_mfma_f32_32x32x16_bf16 v[112:127], v[194:197], v[164:167], v[112:127]
	ds_read_b128 v[240:243], v206 offset:11264
	v_add_f32_e32 v249, v2, v249
	v_add_f32_e32 v251, v3, v251
	v_add_f32_e32 v249, v4, v249
	s_waitcnt lgkmcnt(2)
	v_mfma_f32_32x32x16_bf16 v[112:127], v[252:255], v[160:163], v[112:127]
	ds_read_b128 v[244:247], v206 offset:13312
	v_add_f32_e32 v251, v5, v251
	v_add_f32_e32 v249, v6, v249
	v_add_f32_e32 v251, v7, v251
	s_waitcnt lgkmcnt(2)
	v_mfma_f32_32x32x16_bf16 v[112:127], v[236:239], v[156:159], v[112:127]
	ds_read_b128 v[190:193], v206 offset:15360
	v_cvt_pk_bf16_f32 v232, v8, v9
	v_cvt_pk_bf16_f32 v233, v10, v11
	v_cvt_pk_bf16_f32 v234, v12, v13
	s_waitcnt lgkmcnt(2)
	v_mfma_f32_32x32x16_bf16 v[112:127], v[240:243], v[152:155], v[112:127]
	ds_read_b64_tr_b16 v[194:195], v201 offset:49152
	ds_read_b64_tr_b16 v[196:197], v201 offset:51200
	v_cvt_pk_bf16_f32 v235, v14, v15
	v_add_f32_e32 v249, v8, v249
	v_add_f32_e32 v251, v9, v251
	s_waitcnt lgkmcnt(3)
	v_mfma_f32_32x32x16_bf16 v[112:127], v[244:247], v[148:151], v[112:127]
	ds_read_b64_tr_b16 v[252:253], v201 offset:53248
	ds_read_b64_tr_b16 v[254:255], v201 offset:55296
	v_add_f32_e32 v249, v10, v249
	v_add_f32_e32 v251, v11, v251
	v_add_f32_e32 v249, v12, v249
	s_waitcnt lgkmcnt(4)
	v_mfma_f32_32x32x16_bf16 v[112:127], v[190:193], v[144:147], v[112:127]
	ds_read_b64_tr_b16 v[236:237], v201 offset:57344
	ds_read_b64_tr_b16 v[238:239], v201 offset:59392
	v_add_f32_e32 v251, v13, v251
	v_add_f32_e32 v249, v14, v249
	v_add_f32_e32 v251, v15, v251
	s_waitcnt lgkmcnt(4)
	v_mfma_f32_32x32x16_bf16 v[80:95], v[220:223], v[194:197], v[80:95]
	ds_read_b64_tr_b16 v[240:241], v201 offset:61440
	ds_read_b64_tr_b16 v[242:243], v201 offset:63488
	v_exp_f32_e32 v96, v96
	v_exp_f32_e32 v97, v97
	s_waitcnt lgkmcnt(4)
	v_mfma_f32_32x32x16_bf16 v[80:95], v[224:227], v[252:255], v[80:95]
	ds_read_b64_tr_b16 v[244:245], v201 offset:49664
	ds_read_b64_tr_b16 v[246:247], v201 offset:51712
	v_exp_f32_e32 v98, v98
	v_exp_f32_e32 v99, v99
	s_waitcnt lgkmcnt(4)
	v_mfma_f32_32x32x16_bf16 v[80:95], v[228:231], v[236:239], v[80:95]
	ds_read_b64_tr_b16 v[190:191], v201 offset:53760
	ds_read_b64_tr_b16 v[192:193], v201 offset:55808
	v_exp_f32_e32 v100, v100
	v_exp_f32_e32 v101, v101
	s_waitcnt lgkmcnt(4)
	v_mfma_f32_32x32x16_bf16 v[80:95], v[232:235], v[240:243], v[80:95]
	ds_read_b64_tr_b16 v[194:195], v201 offset:57856
	ds_read_b64_tr_b16 v[196:197], v201 offset:59904
	v_exp_f32_e32 v102, v102
	v_exp_f32_e32 v103, v103
	s_waitcnt lgkmcnt(4)
	v_mfma_f32_32x32x16_bf16 v[64:79], v[220:223], v[244:247], v[64:79]
	ds_read_b64_tr_b16 v[252:253], v201 offset:61952
	ds_read_b64_tr_b16 v[254:255], v201 offset:64000
	v_exp_f32_e32 v104, v104
	v_exp_f32_e32 v105, v105
	s_waitcnt lgkmcnt(4)
	v_mfma_f32_32x32x16_bf16 v[64:79], v[224:227], v[190:193], v[64:79]
	ds_read_b64_tr_b16 v[236:237], v201 offset:50176
	ds_read_b64_tr_b16 v[238:239], v201 offset:52224
	v_exp_f32_e32 v106, v106
	v_exp_f32_e32 v107, v107
	s_waitcnt lgkmcnt(4)
	v_mfma_f32_32x32x16_bf16 v[64:79], v[228:231], v[194:197], v[64:79]
	ds_read_b64_tr_b16 v[240:241], v201 offset:54272
	ds_read_b64_tr_b16 v[242:243], v201 offset:56320
	v_exp_f32_e32 v108, v108
	v_exp_f32_e32 v109, v109
	s_waitcnt lgkmcnt(4)
	v_mfma_f32_32x32x16_bf16 v[64:79], v[232:235], v[252:255], v[64:79]
	ds_read_b64_tr_b16 v[244:245], v201 offset:58368
	ds_read_b64_tr_b16 v[246:247], v201 offset:60416
	v_exp_f32_e32 v110, v110
	v_exp_f32_e32 v111, v111
	s_waitcnt lgkmcnt(4)
	v_mfma_f32_32x32x16_bf16 v[48:63], v[220:223], v[236:239], v[48:63]
	ds_read_b64_tr_b16 v[236:237], v201 offset:62464
	ds_read_b64_tr_b16 v[238:239], v201 offset:64512
	ds_read_b64_tr_b16 v[190:191], v201 offset:54784
	ds_read_b64_tr_b16 v[192:193], v201 offset:56832
	v_exp_f32_e32 v112, v112
	v_exp_f32_e32 v113, v113
	s_waitcnt lgkmcnt(6)
	v_mfma_f32_32x32x16_bf16 v[48:63], v[224:227], v[240:243], v[48:63]
	ds_read_b64_tr_b16 v[240:241], v201 offset:50688
	ds_read_b64_tr_b16 v[242:243], v201 offset:52736
	ds_read_b64_tr_b16 v[194:195], v201 offset:58880
	ds_read_b64_tr_b16 v[196:197], v201 offset:60928
	v_exp_f32_e32 v114, v114
	v_exp_f32_e32 v115, v115
	s_waitcnt lgkmcnt(8)
	v_mfma_f32_32x32x16_bf16 v[48:63], v[228:231], v[244:247], v[48:63]
	ds_read_b64_tr_b16 v[252:253], v201 offset:62976
	ds_read_b64_tr_b16 v[254:255], v201 offset:65024
	v_exp_f32_e32 v116, v116
	v_exp_f32_e32 v117, v117
	s_waitcnt lgkmcnt(8)
	v_mfma_f32_32x32x16_bf16 v[48:63], v[232:235], v[236:239], v[48:63]
	v_exp_f32_e32 v118, v118
	v_exp_f32_e32 v119, v119
	s_waitcnt lgkmcnt(4)
	v_mfma_f32_32x32x16_bf16 v[32:47], v[220:223], v[240:243], v[32:47]
	v_exp_f32_e32 v120, v120
	v_exp_f32_e32 v121, v121
	s_waitcnt vmcnt(8) lgkmcnt(0)
	s_barrier
	ds_read_b128 v[236:239], v206 offset:16384
	ds_read_b128 v[240:243], v206 offset:18432
	ds_read_b128 v[244:247], v206 offset:20480
	v_mfma_f32_32x32x16_bf16 v[32:47], v[224:227], v[190:193], v[32:47]
	v_exp_f32_e32 v122, v122
	v_exp_f32_e32 v123, v123
	v_mfma_f32_32x32x16_bf16 v[32:47], v[228:231], v[194:197], v[32:47]
	v_exp_f32_e32 v124, v124
	v_exp_f32_e32 v125, v125
	v_mfma_f32_32x32x16_bf16 v[32:47], v[232:235], v[252:255], v[32:47]
	v_exp_f32_e32 v126, v126
	v_exp_f32_e32 v127, v127
	s_sub_u32 s98, s98, 1
	s_cmp_lg_u32 s98, 0
	s_cbranch_scc1 .Lattn_loop
	s_waitcnt lgkmcnt(2)
	v_mfma_f32_32x32x16_bf16 v[128:143], v[236:239], v[172:175], v[16:31]
	ds_read_b128 v[190:193], v206 offset:22528
	v_cvt_pk_bf16_f32 v220, v96, v97
	v_cvt_pk_bf16_f32 v221, v98, v99
	v_cvt_pk_bf16_f32 v222, v100, v101
	s_waitcnt lgkmcnt(2)
	v_mfma_f32_32x32x16_bf16 v[128:143], v[240:243], v[168:171], v[128:143]
	ds_read_b128 v[194:197], v206 offset:24576
	v_cvt_pk_bf16_f32 v223, v102, v103
	v_add_f32_e32 v218, v96, v218
	v_add_f32_e32 v248, v97, v248
	s_waitcnt lgkmcnt(2)
	v_mfma_f32_32x32x16_bf16 v[128:143], v[244:247], v[164:167], v[128:143]
	ds_read_b128 v[252:255], v206 offset:26624
	s_add_i32 m0, s68, 49152
	v_add_f32_e32 v218, v98, v218
	v_add_f32_e32 v248, v99, v248
	v_add_f32_e32 v218, v100, v218
	global_load_lds_dwordx4 v199, s[70:71]
	s_waitcnt lgkmcnt(2)
	v_mfma_f32_32x32x16_bf16 v[128:143], v[190:193], v[160:163], v[128:143]
	ds_read_b128 v[236:239], v206 offset:28672
	s_add_i32 m0, s68, 57344
	v_add_f32_e32 v248, v101, v248
	v_add_f32_e32 v218, v102, v218
	v_add_f32_e32 v248, v103, v248
	global_load_lds_dwordx4 v219, s[70:71]
	s_add_u32 s70, s70, 0x90000
	s_addc_u32 s71, s71, 0
	s_waitcnt lgkmcnt(2)
	v_mfma_f32_32x32x16_bf16 v[128:143], v[194:197], v[156:159], v[128:143]
	ds_read_b128 v[240:243], v206 offset:30720
	v_cvt_pk_bf16_f32 v224, v104, v105
	v_cvt_pk_bf16_f32 v225, v106, v107
	v_cvt_pk_bf16_f32 v226, v108, v109
	s_waitcnt lgkmcnt(2)
	v_mfma_f32_32x32x16_bf16 v[128:143], v[252:255], v[152:155], v[128:143]
	ds_read_b128 v[244:247], v206 offset:17408
	v_cvt_pk_bf16_f32 v227, v110, v111
	v_add_f32_e32 v218, v104, v218
	v_add_f32_e32 v248, v105, v248
	s_waitcnt lgkmcnt(2)
	v_mfma_f32_32x32x16_bf16 v[128:143], v[236:239], v[148:151], v[128:143]
	ds_read_b128 v[190:193], v206 offset:19456
	v_add_f32_e32 v218, v106, v218
	v_add_f32_e32 v248, v107, v248
	v_add_f32_e32 v218, v108, v218
	s_waitcnt lgkmcnt(2)
	v_mfma_f32_32x32x16_bf16 v[128:143], v[240:243], v[144:147], v[128:143]
	ds_read_b128 v[194:197], v206 offset:21504
	v_add_f32_e32 v248, v109, v248
	v_add_f32_e32 v218, v110, v218
	v_add_f32_e32 v248, v111, v248
	s_waitcnt lgkmcnt(2)
	v_mfma_f32_32x32x16_bf16 v[0:15], v[244:247], v[172:175], v[16:31]
	ds_read_b128 v[252:255], v206 offset:23552
	v_cvt_pk_bf16_f32 v228, v112, v113
	v_cvt_pk_bf16_f32 v229, v114, v115
	v_cvt_pk_bf16_f32 v230, v116, v117
	s_waitcnt lgkmcnt(2)
	v_mfma_f32_32x32x16_bf16 v[0:15], v[190:193], v[168:171], v[0:15]
	ds_read_b128 v[236:239], v206 offset:25600
	v_cvt_pk_bf16_f32 v231, v118, v119
	v_add_f32_e32 v249, v112, v249
	v_add_f32_e32 v251, v113, v251
	s_waitcnt lgkmcnt(2)
	v_mfma_f32_32x32x16_bf16 v[0:15], v[194:197], v[164:167], v[0:15]
	ds_read_b128 v[240:243], v206 offset:27648
	v_add_f32_e32 v249, v114, v249
	v_add_f32_e32 v251, v115, v251
	v_add_f32_e32 v249, v116, v249
	s_waitcnt lgkmcnt(2)
	v_mfma_f32_32x32x16_bf16 v[0:15], v[252:255], v[160:163], v[0:15]
	ds_read_b128 v[244:247], v206 offset:29696
	v_add_f32_e32 v251, v117, v251
	v_add_f32_e32 v249, v118, v249
	v_add_f32_e32 v251, v119, v251
	s_waitcnt lgkmcnt(2)
	v_mfma_f32_32x32x16_bf16 v[0:15], v[236:239], v[156:159], v[0:15]
	ds_read_b128 v[190:193], v206 offset:31744
	v_cvt_pk_bf16_f32 v232, v120, v121
	v_cvt_pk_bf16_f32 v233, v122, v123
	v_cvt_pk_bf16_f32 v234, v124, v125
	s_waitcnt lgkmcnt(2)
	v_mfma_f32_32x32x16_bf16 v[0:15], v[240:243], v[152:155], v[0:15]
	ds_read_b64_tr_b16 v[194:195], v201 offset:0
	ds_read_b64_tr_b16 v[196:197], v201 offset:2048
	v_cvt_pk_bf16_f32 v235, v126, v127
	v_add_f32_e32 v249, v120, v249
	v_add_f32_e32 v251, v121, v251
	s_waitcnt lgkmcnt(3)
	v_mfma_f32_32x32x16_bf16 v[0:15], v[244:247], v[148:151], v[0:15]
	ds_read_b64_tr_b16 v[252:253], v201 offset:4096
	ds_read_b64_tr_b16 v[254:255], v201 offset:6144
	v_add_f32_e32 v249, v122, v249
	v_add_f32_e32 v251, v123, v251
	v_add_f32_e32 v249, v124, v249
	s_waitcnt lgkmcnt(4)
	v_mfma_f32_32x32x16_bf16 v[0:15], v[190:193], v[144:147], v[0:15]
	ds_read_b64_tr_b16 v[236:237], v201 offset:8192
	ds_read_b64_tr_b16 v[238:239], v201 offset:10240
	v_add_f32_e32 v251, v125, v251
	v_add_f32_e32 v249, v126, v249
	v_add_f32_e32 v251, v127, v251
	s_waitcnt lgkmcnt(4)
	v_mfma_f32_32x32x16_bf16 v[80:95], v[220:223], v[194:197], v[80:95]
	ds_read_b64_tr_b16 v[240:241], v201 offset:12288
	ds_read_b64_tr_b16 v[242:243], v201 offset:14336
	v_exp_f32_e32 v128, v128
	v_exp_f32_e32 v129, v129
	s_waitcnt lgkmcnt(4)
	v_mfma_f32_32x32x16_bf16 v[80:95], v[224:227], v[252:255], v[80:95]
	ds_read_b64_tr_b16 v[244:245], v201 offset:512
	ds_read_b64_tr_b16 v[246:247], v201 offset:2560
	v_exp_f32_e32 v130, v130
	v_exp_f32_e32 v131, v131
	s_waitcnt lgkmcnt(4)
	v_mfma_f32_32x32x16_bf16 v[80:95], v[228:231], v[236:239], v[80:95]
	ds_read_b64_tr_b16 v[190:191], v201 offset:4608
	ds_read_b64_tr_b16 v[192:193], v201 offset:6656
	v_exp_f32_e32 v132, v132
	v_exp_f32_e32 v133, v133
	s_waitcnt lgkmcnt(4)
	v_mfma_f32_32x32x16_bf16 v[80:95], v[232:235], v[240:243], v[80:95]
	ds_read_b64_tr_b16 v[194:195], v201 offset:8704
	ds_read_b64_tr_b16 v[196:197], v201 offset:10752
	v_exp_f32_e32 v134, v134
	v_exp_f32_e32 v135, v135
	s_waitcnt lgkmcnt(4)
	v_mfma_f32_32x32x16_bf16 v[64:79], v[220:223], v[244:247], v[64:79]
	ds_read_b64_tr_b16 v[252:253], v201 offset:12800
	ds_read_b64_tr_b16 v[254:255], v201 offset:14848
	v_exp_f32_e32 v136, v136
	v_exp_f32_e32 v137, v137
	s_waitcnt lgkmcnt(4)
	v_mfma_f32_32x32x16_bf16 v[64:79], v[224:227], v[190:193], v[64:79]
	ds_read_b64_tr_b16 v[236:237], v201 offset:1024
	ds_read_b64_tr_b16 v[238:239], v201 offset:3072
	v_exp_f32_e32 v138, v138
	v_exp_f32_e32 v139, v139
	s_waitcnt lgkmcnt(4)
	v_mfma_f32_32x32x16_bf16 v[64:79], v[228:231], v[194:197], v[64:79]
	ds_read_b64_tr_b16 v[240:241], v201 offset:5120
	ds_read_b64_tr_b16 v[242:243], v201 offset:7168
	v_exp_f32_e32 v140, v140
	v_exp_f32_e32 v141, v141
	s_waitcnt lgkmcnt(4)
	v_mfma_f32_32x32x16_bf16 v[64:79], v[232:235], v[252:255], v[64:79]
	ds_read_b64_tr_b16 v[244:245], v201 offset:9216
	ds_read_b64_tr_b16 v[246:247], v201 offset:11264
	v_exp_f32_e32 v142, v142
	v_exp_f32_e32 v143, v143
	s_waitcnt lgkmcnt(4)
	v_mfma_f32_32x32x16_bf16 v[48:63], v[220:223], v[236:239], v[48:63]
	ds_read_b64_tr_b16 v[236:237], v201 offset:13312
	ds_read_b64_tr_b16 v[238:239], v201 offset:15360
	ds_read_b64_tr_b16 v[190:191], v201 offset:5632
	ds_read_b64_tr_b16 v[192:193], v201 offset:7680
	v_exp_f32_e32 v0, v0
	v_exp_f32_e32 v1, v1
	s_waitcnt lgkmcnt(6)
	v_mfma_f32_32x32x16_bf16 v[48:63], v[224:227], v[240:243], v[48:63]
	ds_read_b64_tr_b16 v[240:241], v201 offset:1536
	ds_read_b64_tr_b16 v[242:243], v201 offset:3584
	ds_read_b64_tr_b16 v[194:195], v201 offset:9728
	ds_read_b64_tr_b16 v[196:197], v201 offset:11776
	v_exp_f32_e32 v2, v2
	v_exp_f32_e32 v3, v3
	s_waitcnt lgkmcnt(8)
	v_mfma_f32_32x32x16_bf16 v[48:63], v[228:231], v[244:247], v[48:63]
	ds_read_b64_tr_b16 v[252:253], v201 offset:13824
	ds_read_b64_tr_b16 v[254:255], v201 offset:15872
	v_exp_f32_e32 v4, v4
	v_exp_f32_e32 v5, v5
	s_waitcnt lgkmcnt(8)
	v_mfma_f32_32x32x16_bf16 v[48:63], v[232:235], v[236:239], v[48:63]
	v_exp_f32_e32 v6, v6
	v_exp_f32_e32 v7, v7
	s_waitcnt lgkmcnt(4)
	v_mfma_f32_32x32x16_bf16 v[32:47], v[220:223], v[240:243], v[32:47]
	v_exp_f32_e32 v8, v8
	v_exp_f32_e32 v9, v9
	s_waitcnt vmcnt(6) lgkmcnt(0)
	s_barrier
	ds_read_b128 v[236:239], v206 offset:32768
	ds_read_b128 v[240:243], v206 offset:34816
	ds_read_b128 v[244:247], v206 offset:36864
	v_mfma_f32_32x32x16_bf16 v[32:47], v[224:227], v[190:193], v[32:47]
	v_exp_f32_e32 v10, v10
	v_exp_f32_e32 v11, v11
	v_mfma_f32_32x32x16_bf16 v[32:47], v[228:231], v[194:197], v[32:47]
	v_exp_f32_e32 v12, v12
	v_exp_f32_e32 v13, v13
	v_mfma_f32_32x32x16_bf16 v[32:47], v[232:235], v[252:255], v[32:47]
	v_exp_f32_e32 v14, v14
	v_exp_f32_e32 v15, v15
	s_waitcnt lgkmcnt(2)
	v_mfma_f32_32x32x16_bf16 v[96:111], v[236:239], v[172:175], v[16:31]
	ds_read_b128 v[190:193], v206 offset:38912
	v_cvt_pk_bf16_f32 v220, v128, v129
	v_cvt_pk_bf16_f32 v221, v130, v131
	v_cvt_pk_bf16_f32 v222, v132, v133
	s_waitcnt lgkmcnt(2)
	v_mfma_f32_32x32x16_bf16 v[96:111], v[240:243], v[168:171], v[96:111]
	ds_read_b128 v[194:197], v206 offset:40960
	v_cvt_pk_bf16_f32 v223, v134, v135
	v_add_f32_e32 v218, v128, v218
	v_add_f32_e32 v248, v129, v248
	s_waitcnt lgkmcnt(2)
	v_mfma_f32_32x32x16_bf16 v[96:111], v[244:247], v[164:167], v[96:111]
	ds_read_b128 v[252:255], v206 offset:43008
	v_add_f32_e32 v218, v130, v218
	v_add_f32_e32 v248, v131, v248
	v_add_f32_e32 v218, v132, v218
	s_waitcnt lgkmcnt(2)
	v_mfma_f32_32x32x16_bf16 v[96:111], v[190:193], v[160:163], v[96:111]
	ds_read_b128 v[236:239], v206 offset:45056
	v_add_f32_e32 v248, v133, v248
	v_add_f32_e32 v218, v134, v218
	v_add_f32_e32 v248, v135, v248
	s_waitcnt lgkmcnt(2)
	v_mfma_f32_32x32x16_bf16 v[96:111], v[194:197], v[156:159], v[96:111]
	ds_read_b128 v[240:243], v206 offset:47104
	v_cvt_pk_bf16_f32 v224, v136, v137
	v_cvt_pk_bf16_f32 v225, v138, v139
	v_cvt_pk_bf16_f32 v226, v140, v141
	s_waitcnt lgkmcnt(2)
	v_mfma_f32_32x32x16_bf16 v[96:111], v[252:255], v[152:155], v[96:111]
	ds_read_b128 v[244:247], v206 offset:33792
	v_cvt_pk_bf16_f32 v227, v142, v143
	v_add_f32_e32 v218, v136, v218
	v_add_f32_e32 v248, v137, v248
	s_waitcnt lgkmcnt(2)
	v_mfma_f32_32x32x16_bf16 v[96:111], v[236:239], v[148:151], v[96:111]
	ds_read_b128 v[190:193], v206 offset:35840
	v_add_f32_e32 v218, v138, v218
	v_add_f32_e32 v248, v139, v248
	v_add_f32_e32 v218, v140, v218
	s_waitcnt lgkmcnt(2)
	v_mfma_f32_32x32x16_bf16 v[96:111], v[240:243], v[144:147], v[96:111]
	ds_read_b128 v[194:197], v206 offset:37888
	v_add_f32_e32 v248, v141, v248
	v_add_f32_e32 v218, v142, v218
	v_add_f32_e32 v248, v143, v248
	s_waitcnt lgkmcnt(2)
	v_mfma_f32_32x32x16_bf16 v[112:127], v[244:247], v[172:175], v[16:31]
	ds_read_b128 v[252:255], v206 offset:39936
	v_cvt_pk_bf16_f32 v228, v0, v1
	v_cvt_pk_bf16_f32 v229, v2, v3
	v_cvt_pk_bf16_f32 v230, v4, v5
	s_waitcnt lgkmcnt(2)
	v_mfma_f32_32x32x16_bf16 v[112:127], v[190:193], v[168:171], v[112:127]
	ds_read_b128 v[236:239], v206 offset:41984
	v_cvt_pk_bf16_f32 v231, v6, v7
	v_add_f32_e32 v249, v0, v249
	v_add_f32_e32 v251, v1, v251
	s_waitcnt lgkmcnt(2)
	v_mfma_f32_32x32x16_bf16 v[112:127], v[194:197], v[164:167], v[112:127]
	ds_read_b128 v[240:243], v206 offset:44032
	v_add_f32_e32 v249, v2, v249
	v_add_f32_e32 v251, v3, v251
	v_add_f32_e32 v249, v4, v249
	s_waitcnt lgkmcnt(2)
	v_mfma_f32_32x32x16_bf16 v[112:127], v[252:255], v[160:163], v[112:127]
	ds_read_b128 v[244:247], v206 offset:46080
	v_add_f32_e32 v251, v5, v251
	v_add_f32_e32 v249, v6, v249
	v_add_f32_e32 v251, v7, v251
	s_waitcnt lgkmcnt(2)
	v_mfma_f32_32x32x16_bf16 v[112:127], v[236:239], v[156:159], v[112:127]
	ds_read_b128 v[190:193], v206 offset:48128
	v_cvt_pk_bf16_f32 v232, v8, v9
	v_cvt_pk_bf16_f32 v233, v10, v11
	v_cvt_pk_bf16_f32 v234, v12, v13
	s_waitcnt lgkmcnt(2)
	v_mfma_f32_32x32x16_bf16 v[112:127], v[240:243], v[152:155], v[112:127]
	ds_read_b64_tr_b16 v[194:195], v201 offset:16384
	ds_read_b64_tr_b16 v[196:197], v201 offset:18432
	v_cvt_pk_bf16_f32 v235, v14, v15
	v_add_f32_e32 v249, v8, v249
	v_add_f32_e32 v251, v9, v251
	s_waitcnt lgkmcnt(3)
	v_mfma_f32_32x32x16_bf16 v[112:127], v[244:247], v[148:151], v[112:127]
	ds_read_b64_tr_b16 v[252:253], v201 offset:20480
	ds_read_b64_tr_b16 v[254:255], v201 offset:22528
	v_add_f32_e32 v249, v10, v249
	v_add_f32_e32 v251, v11, v251
	v_add_f32_e32 v249, v12, v249
	s_waitcnt lgkmcnt(4)
	v_mfma_f32_32x32x16_bf16 v[112:127], v[190:193], v[144:147], v[112:127]
	ds_read_b64_tr_b16 v[236:237], v201 offset:24576
	ds_read_b64_tr_b16 v[238:239], v201 offset:26624
	v_add_f32_e32 v251, v13, v251
	v_add_f32_e32 v249, v14, v249
	v_add_f32_e32 v251, v15, v251
	s_waitcnt lgkmcnt(4)
	v_mfma_f32_32x32x16_bf16 v[80:95], v[220:223], v[194:197], v[80:95]
	ds_read_b64_tr_b16 v[240:241], v201 offset:28672
	ds_read_b64_tr_b16 v[242:243], v201 offset:30720
	v_exp_f32_e32 v96, v96
	v_exp_f32_e32 v97, v97
	s_waitcnt lgkmcnt(4)
	v_mfma_f32_32x32x16_bf16 v[80:95], v[224:227], v[252:255], v[80:95]
	ds_read_b64_tr_b16 v[244:245], v201 offset:16896
	ds_read_b64_tr_b16 v[246:247], v201 offset:18944
	v_exp_f32_e32 v98, v98
	v_exp_f32_e32 v99, v99
	s_waitcnt lgkmcnt(4)
	v_mfma_f32_32x32x16_bf16 v[80:95], v[228:231], v[236:239], v[80:95]
	ds_read_b64_tr_b16 v[190:191], v201 offset:20992
	ds_read_b64_tr_b16 v[192:193], v201 offset:23040
	v_exp_f32_e32 v100, v100
	v_exp_f32_e32 v101, v101
	s_waitcnt lgkmcnt(4)
	v_mfma_f32_32x32x16_bf16 v[80:95], v[232:235], v[240:243], v[80:95]
	ds_read_b64_tr_b16 v[194:195], v201 offset:25088
	ds_read_b64_tr_b16 v[196:197], v201 offset:27136
	v_exp_f32_e32 v102, v102
	v_exp_f32_e32 v103, v103
	s_waitcnt lgkmcnt(4)
	v_mfma_f32_32x32x16_bf16 v[64:79], v[220:223], v[244:247], v[64:79]
	ds_read_b64_tr_b16 v[252:253], v201 offset:29184
	ds_read_b64_tr_b16 v[254:255], v201 offset:31232
	v_exp_f32_e32 v104, v104
	v_exp_f32_e32 v105, v105
	s_waitcnt lgkmcnt(4)
	v_mfma_f32_32x32x16_bf16 v[64:79], v[224:227], v[190:193], v[64:79]
	ds_read_b64_tr_b16 v[236:237], v201 offset:17408
	ds_read_b64_tr_b16 v[238:239], v201 offset:19456
	v_exp_f32_e32 v106, v106
	v_exp_f32_e32 v107, v107
	s_waitcnt lgkmcnt(4)
	v_mfma_f32_32x32x16_bf16 v[64:79], v[228:231], v[194:197], v[64:79]
	ds_read_b64_tr_b16 v[240:241], v201 offset:21504
	ds_read_b64_tr_b16 v[242:243], v201 offset:23552
	v_exp_f32_e32 v108, v108
	v_exp_f32_e32 v109, v109
	s_waitcnt lgkmcnt(4)
	v_mfma_f32_32x32x16_bf16 v[64:79], v[232:235], v[252:255], v[64:79]
	ds_read_b64_tr_b16 v[244:245], v201 offset:25600
	ds_read_b64_tr_b16 v[246:247], v201 offset:27648
	v_exp_f32_e32 v110, v110
	v_exp_f32_e32 v111, v111
	s_waitcnt lgkmcnt(4)
	v_mfma_f32_32x32x16_bf16 v[48:63], v[220:223], v[236:239], v[48:63]
	ds_read_b64_tr_b16 v[236:237], v201 offset:29696
	ds_read_b64_tr_b16 v[238:239], v201 offset:31744
	ds_read_b64_tr_b16 v[190:191], v201 offset:22016
	ds_read_b64_tr_b16 v[192:193], v201 offset:24064
	v_exp_f32_e32 v112, v112
	v_exp_f32_e32 v113, v113
	s_waitcnt lgkmcnt(6)
	v_mfma_f32_32x32x16_bf16 v[48:63], v[224:227], v[240:243], v[48:63]
	ds_read_b64_tr_b16 v[240:241], v201 offset:17920
	ds_read_b64_tr_b16 v[242:243], v201 offset:19968
	ds_read_b64_tr_b16 v[194:195], v201 offset:26112
	ds_read_b64_tr_b16 v[196:197], v201 offset:28160
	v_exp_f32_e32 v114, v114
	v_exp_f32_e32 v115, v115
	s_waitcnt lgkmcnt(8)
	v_mfma_f32_32x32x16_bf16 v[48:63], v[228:231], v[244:247], v[48:63]
	ds_read_b64_tr_b16 v[252:253], v201 offset:30208
	ds_read_b64_tr_b16 v[254:255], v201 offset:32256
	v_exp_f32_e32 v116, v116
	v_exp_f32_e32 v117, v117
	s_waitcnt lgkmcnt(8)
	v_mfma_f32_32x32x16_bf16 v[48:63], v[232:235], v[236:239], v[48:63]
	v_exp_f32_e32 v118, v118
	v_exp_f32_e32 v119, v119
	s_waitcnt lgkmcnt(4)
	v_mfma_f32_32x32x16_bf16 v[32:47], v[220:223], v[240:243], v[32:47]
	v_exp_f32_e32 v120, v120
	v_exp_f32_e32 v121, v121
	s_waitcnt vmcnt(2) lgkmcnt(0)
	s_barrier
	ds_read_b128 v[236:239], v206 offset:49152
	ds_read_b128 v[240:243], v206 offset:51200
	ds_read_b128 v[244:247], v206 offset:53248
	v_mfma_f32_32x32x16_bf16 v[32:47], v[224:227], v[190:193], v[32:47]
	v_exp_f32_e32 v122, v122
	v_exp_f32_e32 v123, v123
	v_mfma_f32_32x32x16_bf16 v[32:47], v[228:231], v[194:197], v[32:47]
	v_exp_f32_e32 v124, v124
	v_exp_f32_e32 v125, v125
	v_mfma_f32_32x32x16_bf16 v[32:47], v[232:235], v[252:255], v[32:47]
	v_exp_f32_e32 v126, v126
	v_exp_f32_e32 v127, v127
	s_waitcnt lgkmcnt(2)
	v_mfma_f32_32x32x16_bf16 v[128:143], v[236:239], v[172:175], v[16:31]
	ds_read_b128 v[190:193], v206 offset:55296
	v_cvt_pk_bf16_f32 v220, v96, v97
	v_cvt_pk_bf16_f32 v221, v98, v99
	v_cvt_pk_bf16_f32 v222, v100, v101
	s_waitcnt lgkmcnt(2)
	v_mfma_f32_32x32x16_bf16 v[128:143], v[240:243], v[168:171], v[128:143]
	ds_read_b128 v[194:197], v206 offset:57344
	v_cvt_pk_bf16_f32 v223, v102, v103
	v_add_f32_e32 v218, v96, v218
	v_add_f32_e32 v248, v97, v248
	s_waitcnt lgkmcnt(2)
	v_mfma_f32_32x32x16_bf16 v[128:143], v[244:247], v[164:167], v[128:143]
	ds_read_b128 v[252:255], v206 offset:59392
	v_add_f32_e32 v218, v98, v218
	v_add_f32_e32 v248, v99, v248
	v_add_f32_e32 v218, v100, v218
	s_waitcnt lgkmcnt(2)
	v_mfma_f32_32x32x16_bf16 v[128:143], v[190:193], v[160:163], v[128:143]
	ds_read_b128 v[236:239], v206 offset:61440
	v_add_f32_e32 v248, v101, v248
	v_add_f32_e32 v218, v102, v218
	v_add_f32_e32 v248, v103, v248
	s_waitcnt lgkmcnt(2)
	v_mfma_f32_32x32x16_bf16 v[128:143], v[194:197], v[156:159], v[128:143]
	ds_read_b128 v[240:243], v206 offset:63488
	v_cvt_pk_bf16_f32 v224, v104, v105
	v_cvt_pk_bf16_f32 v225, v106, v107
	v_cvt_pk_bf16_f32 v226, v108, v109
	s_waitcnt lgkmcnt(2)
	v_mfma_f32_32x32x16_bf16 v[128:143], v[252:255], v[152:155], v[128:143]
	ds_read_b128 v[244:247], v206 offset:50176
	v_cvt_pk_bf16_f32 v227, v110, v111
	v_add_f32_e32 v218, v104, v218
	v_add_f32_e32 v248, v105, v248
	s_waitcnt lgkmcnt(2)
	v_mfma_f32_32x32x16_bf16 v[128:143], v[236:239], v[148:151], v[128:143]
	ds_read_b128 v[190:193], v206 offset:52224
	v_add_f32_e32 v218, v106, v218
	v_add_f32_e32 v248, v107, v248
	v_add_f32_e32 v218, v108, v218
	s_waitcnt lgkmcnt(2)
	v_mfma_f32_32x32x16_bf16 v[128:143], v[240:243], v[144:147], v[128:143]
	ds_read_b128 v[194:197], v206 offset:54272
	v_add_f32_e32 v248, v109, v248
	v_add_f32_e32 v218, v110, v218
	v_add_f32_e32 v248, v111, v248
	s_waitcnt lgkmcnt(2)
	v_mfma_f32_32x32x16_bf16 v[0:15], v[244:247], v[172:175], v[16:31]
	ds_read_b128 v[252:255], v206 offset:56320
	v_cvt_pk_bf16_f32 v228, v112, v113
	v_cvt_pk_bf16_f32 v229, v114, v115
	v_cvt_pk_bf16_f32 v230, v116, v117
	s_waitcnt lgkmcnt(2)
	v_mfma_f32_32x32x16_bf16 v[0:15], v[190:193], v[168:171], v[0:15]
	ds_read_b128 v[236:239], v206 offset:58368
	v_cvt_pk_bf16_f32 v231, v118, v119
	v_add_f32_e32 v249, v112, v249
	v_add_f32_e32 v251, v113, v251
	s_waitcnt lgkmcnt(2)
	v_mfma_f32_32x32x16_bf16 v[0:15], v[194:197], v[164:167], v[0:15]
	ds_read_b128 v[240:243], v206 offset:60416
	v_add_f32_e32 v249, v114, v249
	v_add_f32_e32 v251, v115, v251
	v_add_f32_e32 v249, v116, v249
	s_waitcnt lgkmcnt(2)
	v_mfma_f32_32x32x16_bf16 v[0:15], v[252:255], v[160:163], v[0:15]
	ds_read_b128 v[244:247], v206 offset:62464
	v_add_f32_e32 v251, v117, v251
	v_add_f32_e32 v249, v118, v249
	v_add_f32_e32 v251, v119, v251
	s_waitcnt lgkmcnt(2)
	v_mfma_f32_32x32x16_bf16 v[0:15], v[236:239], v[156:159], v[0:15]
	ds_read_b128 v[190:193], v206 offset:64512
	v_cvt_pk_bf16_f32 v232, v120, v121
	v_cvt_pk_bf16_f32 v233, v122, v123
	v_cvt_pk_bf16_f32 v234, v124, v125
	s_waitcnt lgkmcnt(2)
	v_mfma_f32_32x32x16_bf16 v[0:15], v[240:243], v[152:155], v[0:15]
	ds_read_b64_tr_b16 v[194:195], v201 offset:32768
	ds_read_b64_tr_b16 v[196:197], v201 offset:34816
	v_cvt_pk_bf16_f32 v235, v126, v127
	v_add_f32_e32 v249, v120, v249
	v_add_f32_e32 v251, v121, v251
	s_waitcnt lgkmcnt(3)
	v_mfma_f32_32x32x16_bf16 v[0:15], v[244:247], v[148:151], v[0:15]
	ds_read_b64_tr_b16 v[252:253], v201 offset:36864
	ds_read_b64_tr_b16 v[254:255], v201 offset:38912
	v_add_f32_e32 v249, v122, v249
	v_add_f32_e32 v251, v123, v251
	v_add_f32_e32 v249, v124, v249
	s_waitcnt lgkmcnt(4)
	v_mfma_f32_32x32x16_bf16 v[0:15], v[190:193], v[144:147], v[0:15]
	ds_read_b64_tr_b16 v[236:237], v201 offset:40960
	ds_read_b64_tr_b16 v[238:239], v201 offset:43008
	v_add_f32_e32 v251, v125, v251
	v_add_f32_e32 v249, v126, v249
	v_add_f32_e32 v251, v127, v251
	s_waitcnt lgkmcnt(4)
	v_mfma_f32_32x32x16_bf16 v[80:95], v[220:223], v[194:197], v[80:95]
	ds_read_b64_tr_b16 v[240:241], v201 offset:45056
	ds_read_b64_tr_b16 v[242:243], v201 offset:47104
	v_exp_f32_e32 v128, v128
	v_exp_f32_e32 v129, v129
	s_waitcnt lgkmcnt(4)
	v_mfma_f32_32x32x16_bf16 v[80:95], v[224:227], v[252:255], v[80:95]
	ds_read_b64_tr_b16 v[244:245], v201 offset:33280
	ds_read_b64_tr_b16 v[246:247], v201 offset:35328
	v_exp_f32_e32 v130, v130
	v_exp_f32_e32 v131, v131
	s_waitcnt lgkmcnt(4)
	v_mfma_f32_32x32x16_bf16 v[80:95], v[228:231], v[236:239], v[80:95]
	ds_read_b64_tr_b16 v[190:191], v201 offset:37376
	ds_read_b64_tr_b16 v[192:193], v201 offset:39424
	v_exp_f32_e32 v132, v132
	v_exp_f32_e32 v133, v133
	s_waitcnt lgkmcnt(4)
	v_mfma_f32_32x32x16_bf16 v[80:95], v[232:235], v[240:243], v[80:95]
	ds_read_b64_tr_b16 v[194:195], v201 offset:41472
	ds_read_b64_tr_b16 v[196:197], v201 offset:43520
	v_exp_f32_e32 v134, v134
	v_exp_f32_e32 v135, v135
	s_waitcnt lgkmcnt(4)
	v_mfma_f32_32x32x16_bf16 v[64:79], v[220:223], v[244:247], v[64:79]
	ds_read_b64_tr_b16 v[252:253], v201 offset:45568
	ds_read_b64_tr_b16 v[254:255], v201 offset:47616
	v_exp_f32_e32 v136, v136
	v_exp_f32_e32 v137, v137
	s_waitcnt lgkmcnt(4)
	v_mfma_f32_32x32x16_bf16 v[64:79], v[224:227], v[190:193], v[64:79]
	ds_read_b64_tr_b16 v[236:237], v201 offset:33792
	ds_read_b64_tr_b16 v[238:239], v201 offset:35840
	v_exp_f32_e32 v138, v138
	v_exp_f32_e32 v139, v139
	s_waitcnt lgkmcnt(4)
	v_mfma_f32_32x32x16_bf16 v[64:79], v[228:231], v[194:197], v[64:79]
	ds_read_b64_tr_b16 v[240:241], v201 offset:37888
	ds_read_b64_tr_b16 v[242:243], v201 offset:39936
	v_exp_f32_e32 v140, v140
	v_exp_f32_e32 v141, v141
	s_waitcnt lgkmcnt(4)
	v_mfma_f32_32x32x16_bf16 v[64:79], v[232:235], v[252:255], v[64:79]
	ds_read_b64_tr_b16 v[244:245], v201 offset:41984
	ds_read_b64_tr_b16 v[246:247], v201 offset:44032
	v_exp_f32_e32 v142, v142
	v_exp_f32_e32 v143, v143
	s_waitcnt lgkmcnt(4)
	v_mfma_f32_32x32x16_bf16 v[48:63], v[220:223], v[236:239], v[48:63]
	ds_read_b64_tr_b16 v[236:237], v201 offset:46080
	ds_read_b64_tr_b16 v[238:239], v201 offset:48128
	ds_read_b64_tr_b16 v[190:191], v201 offset:38400
	ds_read_b64_tr_b16 v[192:193], v201 offset:40448
	v_exp_f32_e32 v0, v0
	v_exp_f32_e32 v1, v1
	s_waitcnt lgkmcnt(6)
	v_mfma_f32_32x32x16_bf16 v[48:63], v[224:227], v[240:243], v[48:63]
	ds_read_b64_tr_b16 v[240:241], v201 offset:34304
	ds_read_b64_tr_b16 v[242:243], v201 offset:36352
	ds_read_b64_tr_b16 v[194:195], v201 offset:42496
	ds_read_b64_tr_b16 v[196:197], v201 offset:44544
	v_exp_f32_e32 v2, v2
	v_exp_f32_e32 v3, v3
	s_waitcnt lgkmcnt(8)
	v_mfma_f32_32x32x16_bf16 v[48:63], v[228:231], v[244:247], v[48:63]
	ds_read_b64_tr_b16 v[252:253], v201 offset:46592
	ds_read_b64_tr_b16 v[254:255], v201 offset:48640
	v_exp_f32_e32 v4, v4
	v_exp_f32_e32 v5, v5
	s_waitcnt lgkmcnt(8)
	v_mfma_f32_32x32x16_bf16 v[48:63], v[232:235], v[236:239], v[48:63]
	v_exp_f32_e32 v6, v6
	v_exp_f32_e32 v7, v7
	s_waitcnt lgkmcnt(4)
	v_mfma_f32_32x32x16_bf16 v[32:47], v[220:223], v[240:243], v[32:47]
	v_exp_f32_e32 v8, v8
	v_exp_f32_e32 v9, v9
	s_waitcnt vmcnt(0) lgkmcnt(0)
	s_barrier
	v_mfma_f32_32x32x16_bf16 v[32:47], v[224:227], v[190:193], v[32:47]
	v_exp_f32_e32 v10, v10
	v_exp_f32_e32 v11, v11
	v_mfma_f32_32x32x16_bf16 v[32:47], v[228:231], v[194:197], v[32:47]
	v_exp_f32_e32 v12, v12
	v_exp_f32_e32 v13, v13
	v_mfma_f32_32x32x16_bf16 v[32:47], v[232:235], v[252:255], v[32:47]
	v_exp_f32_e32 v14, v14
	v_exp_f32_e32 v15, v15
	ds_read_b64_tr_b16 v[194:195], v201 offset:49152
	ds_read_b64_tr_b16 v[196:197], v201 offset:51200
	ds_read_b64_tr_b16 v[252:253], v201 offset:53248
	ds_read_b64_tr_b16 v[254:255], v201 offset:55296
	ds_read_b64_tr_b16 v[236:237], v201 offset:57344
	ds_read_b64_tr_b16 v[238:239], v201 offset:59392
	v_cvt_pk_bf16_f32 v220, v128, v129
	v_cvt_pk_bf16_f32 v221, v130, v131
	v_cvt_pk_bf16_f32 v222, v132, v133
	v_cvt_pk_bf16_f32 v223, v134, v135
	v_add_f32_e32 v218, v128, v218
	v_add_f32_e32 v248, v129, v248
	v_add_f32_e32 v218, v130, v218
	v_add_f32_e32 v248, v131, v248
	v_add_f32_e32 v218, v132, v218
	v_add_f32_e32 v248, v133, v248
	v_add_f32_e32 v218, v134, v218
	v_add_f32_e32 v248, v135, v248
	v_cvt_pk_bf16_f32 v224, v136, v137
	v_cvt_pk_bf16_f32 v225, v138, v139
	v_cvt_pk_bf16_f32 v226, v140, v141
	v_cvt_pk_bf16_f32 v227, v142, v143
	v_add_f32_e32 v218, v136, v218
	v_add_f32_e32 v248, v137, v248
	v_add_f32_e32 v218, v138, v218
	v_add_f32_e32 v248, v139, v248
	v_add_f32_e32 v218, v140, v218
	v_add_f32_e32 v248, v141, v248
	v_add_f32_e32 v218, v142, v218
	v_add_f32_e32 v248, v143, v248
	v_cvt_pk_bf16_f32 v228, v0, v1
	v_cvt_pk_bf16_f32 v229, v2, v3
	v_cvt_pk_bf16_f32 v230, v4, v5
	v_cvt_pk_bf16_f32 v231, v6, v7
	v_add_f32_e32 v249, v0, v249
	v_add_f32_e32 v251, v1, v251
	v_add_f32_e32 v249, v2, v249
	v_add_f32_e32 v251, v3, v251
	v_add_f32_e32 v249, v4, v249
	v_add_f32_e32 v251, v5, v251
	v_add_f32_e32 v249, v6, v249
	v_add_f32_e32 v251, v7, v251
	v_cvt_pk_bf16_f32 v232, v8, v9
	v_cvt_pk_bf16_f32 v233, v10, v11
	v_cvt_pk_bf16_f32 v234, v12, v13
	v_cvt_pk_bf16_f32 v235, v14, v15
	v_add_f32_e32 v249, v8, v249
	v_add_f32_e32 v251, v9, v251
	v_add_f32_e32 v249, v10, v249
	v_add_f32_e32 v251, v11, v251
	v_add_f32_e32 v249, v12, v249
	v_add_f32_e32 v251, v13, v251
	v_add_f32_e32 v249, v14, v249
	v_add_f32_e32 v251, v15, v251
	s_nop 1
	s_waitcnt lgkmcnt(4)
	v_mfma_f32_32x32x16_bf16 v[80:95], v[220:223], v[194:197], v[80:95]
	ds_read_b64_tr_b16 v[240:241], v201 offset:61440
	ds_read_b64_tr_b16 v[242:243], v201 offset:63488
	s_waitcnt lgkmcnt(4)
	v_mfma_f32_32x32x16_bf16 v[80:95], v[224:227], v[252:255], v[80:95]
	ds_read_b64_tr_b16 v[244:245], v201 offset:49664
	ds_read_b64_tr_b16 v[246:247], v201 offset:51712
	s_waitcnt lgkmcnt(4)
	v_mfma_f32_32x32x16_bf16 v[80:95], v[228:231], v[236:239], v[80:95]
	ds_read_b64_tr_b16 v[190:191], v201 offset:53760
	ds_read_b64_tr_b16 v[192:193], v201 offset:55808
	s_waitcnt lgkmcnt(4)
	v_mfma_f32_32x32x16_bf16 v[80:95], v[232:235], v[240:243], v[80:95]
	ds_read_b64_tr_b16 v[194:195], v201 offset:57856
	ds_read_b64_tr_b16 v[196:197], v201 offset:59904
	s_waitcnt lgkmcnt(4)
	v_mfma_f32_32x32x16_bf16 v[64:79], v[220:223], v[244:247], v[64:79]
	ds_read_b64_tr_b16 v[252:253], v201 offset:61952
	ds_read_b64_tr_b16 v[254:255], v201 offset:64000
	s_waitcnt lgkmcnt(4)
	v_mfma_f32_32x32x16_bf16 v[64:79], v[224:227], v[190:193], v[64:79]
	ds_read_b64_tr_b16 v[236:237], v201 offset:50176
	ds_read_b64_tr_b16 v[238:239], v201 offset:52224
	s_waitcnt lgkmcnt(4)
	v_mfma_f32_32x32x16_bf16 v[64:79], v[228:231], v[194:197], v[64:79]
	ds_read_b64_tr_b16 v[240:241], v201 offset:54272
	ds_read_b64_tr_b16 v[242:243], v201 offset:56320
	s_waitcnt lgkmcnt(4)
	v_mfma_f32_32x32x16_bf16 v[64:79], v[232:235], v[252:255], v[64:79]
	ds_read_b64_tr_b16 v[244:245], v201 offset:58368
	ds_read_b64_tr_b16 v[246:247], v201 offset:60416
	s_waitcnt lgkmcnt(4)
	v_mfma_f32_32x32x16_bf16 v[48:63], v[220:223], v[236:239], v[48:63]
	ds_read_b64_tr_b16 v[236:237], v201 offset:62464
	ds_read_b64_tr_b16 v[238:239], v201 offset:64512
	ds_read_b64_tr_b16 v[190:191], v201 offset:54784
	ds_read_b64_tr_b16 v[192:193], v201 offset:56832
	s_waitcnt lgkmcnt(6)
	v_mfma_f32_32x32x16_bf16 v[48:63], v[224:227], v[240:243], v[48:63]
	ds_read_b64_tr_b16 v[240:241], v201 offset:50688
	ds_read_b64_tr_b16 v[242:243], v201 offset:52736
	ds_read_b64_tr_b16 v[194:195], v201 offset:58880
	ds_read_b64_tr_b16 v[196:197], v201 offset:60928
	s_waitcnt lgkmcnt(8)
	v_mfma_f32_32x32x16_bf16 v[48:63], v[228:231], v[244:247], v[48:63]
	ds_read_b64_tr_b16 v[252:253], v201 offset:62976
	ds_read_b64_tr_b16 v[254:255], v201 offset:65024
	s_waitcnt lgkmcnt(8)
	v_mfma_f32_32x32x16_bf16 v[48:63], v[232:235], v[236:239], v[48:63]
	s_waitcnt lgkmcnt(4)
	v_mfma_f32_32x32x16_bf16 v[32:47], v[220:223], v[240:243], v[32:47]
	v_mfma_f32_32x32x16_bf16 v[32:47], v[224:227], v[190:193], v[32:47]
	s_waitcnt lgkmcnt(2)
	v_mfma_f32_32x32x16_bf16 v[32:47], v[228:231], v[194:197], v[32:47]
	s_waitcnt lgkmcnt(0)
	v_mfma_f32_32x32x16_bf16 v[32:47], v[232:235], v[252:255], v[32:47]
	v_add_f32_e32 v218, v218, v248
	v_add_f32_e32 v249, v249, v251
	s_and_b32 s0, s97, 0x3fffffc0
	s_lshl_b32 s0, s0, 2
	v_add_f32_e32 v236, v218, v249
	s_add_i32 s33, s0, 0x20010
	v_mov_b32_e32 v237, v236
	v_lshl_add_u32 v240, v178, 2, s33
	s_nop 1
	v_permlane32_swap_b32_e32 v236, v237
	v_mov_b32_e32 v0, 0
	v_mov_b32_e32 v1, 0
	v_mov_b32_e32 v2, 0
	v_mov_b32_e32 v3, 0
	v_mov_b32_e32 v4, 0
	v_mov_b32_e32 v5, 0
	v_mov_b32_e32 v6, 0
	v_mov_b32_e32 v7, 0
	v_mov_b32_e32 v8, 0
	v_mov_b32_e32 v9, 0
	v_mov_b32_e32 v10, 0
	v_mov_b32_e32 v11, 0
	v_mov_b32_e32 v12, 0
	v_mov_b32_e32 v13, 0
	v_mov_b32_e32 v14, 0
	v_mov_b32_e32 v15, 0
	v_add_f32_e32 v236, v236, v237
	s_and_saveexec_b64 s[0:1], vcc
	ds_write_b32 v240, v236
	s_branch .LBB0_236

	.amdhsa_kernel _Z10hybrid_fwd4Args
		.amdhsa_group_segment_fixed_size 16
		.amdhsa_private_segment_fixed_size 0
		.amdhsa_kernarg_size 400
		.amdhsa_user_sgpr_count 2
		.amdhsa_user_sgpr_dispatch_ptr 0
		.amdhsa_user_sgpr_queue_ptr 0
		.amdhsa_user_sgpr_kernarg_segment_ptr 1
		.amdhsa_user_sgpr_dispatch_id 0
		.amdhsa_user_sgpr_kernarg_preload_length 0
		.amdhsa_user_sgpr_kernarg_preload_offset 0
		.amdhsa_user_sgpr_private_segment_size 0
		.amdhsa_uses_dynamic_stack 0
		.amdhsa_enable_private_segment 0
		.amdhsa_system_sgpr_workgroup_id_x 1
		.amdhsa_system_sgpr_workgroup_id_y 0
		.amdhsa_system_sgpr_workgroup_id_z 0
		.amdhsa_system_sgpr_workgroup_info 0
		.amdhsa_system_vgpr_workitem_id 2
		.amdhsa_next_free_vgpr 256
		.amdhsa_next_free_sgpr 99
		.amdhsa_accum_offset 256
		.amdhsa_reserve_vcc 1
		.amdhsa_float_round_mode_32 0
		.amdhsa_float_round_mode_16_64 0
		.amdhsa_float_denorm_mode_32 3
		.amdhsa_float_denorm_mode_16_64 3
		.amdhsa_dx10_clamp 1
		.amdhsa_ieee_mode 1
		.amdhsa_fp16_overflow 0
		.amdhsa_tg_split 0
		.amdhsa_exception_fp_ieee_invalid_op 0
		.amdhsa_exception_fp_denorm_src 0
		.amdhsa_exception_fp_ieee_div_zero 0
		.amdhsa_exception_fp_ieee_overflow 0
		.amdhsa_exception_fp_ieee_underflow 0
		.amdhsa_exception_fp_ieee_inexact 0
		.amdhsa_exception_int_div_zero 0
	.end_amdhsa_kernel

.Lfunc_end0:
	.size	_Z10hybrid_fwd4Args, .Lfunc_end0-_Z10hybrid_fwd4Args
	.set _Z10hybrid_fwd4Args.num_vgpr, 256
	.set _Z10hybrid_fwd4Args.num_agpr, 0
	.set _Z10hybrid_fwd4Args.numbered_sgpr, 99
	.set _Z10hybrid_fwd4Args.num_named_barrier, 0
	.set _Z10hybrid_fwd4Args.private_seg_size, 0
	.set _Z10hybrid_fwd4Args.uses_vcc, 1
	.set _Z10hybrid_fwd4Args.uses_flat_scratch, 0
	.set _Z10hybrid_fwd4Args.has_dyn_sized_stack, 0
	.set _Z10hybrid_fwd4Args.has_recursion, 0
	.set _Z10hybrid_fwd4Args.has_indirect_call, 0

amdhsa.kernels:
  - .agpr_count:     0
    .args:
      - .offset:         0
        .size:           144
        .value_kind:     by_value
      - .offset:         144
        .size:           4
        .value_kind:     hidden_block_count_x
      - .offset:         148
        .size:           4
        .value_kind:     hidden_block_count_y
      - .offset:         152
        .size:           4
        .value_kind:     hidden_block_count_z
      - .offset:         156
        .size:           2
        .value_kind:     hidden_group_size_x
      - .offset:         158
        .size:           2
        .value_kind:     hidden_group_size_y
      - .offset:         160
        .size:           2
        .value_kind:     hidden_group_size_z
      - .offset:         162
        .size:           2
        .value_kind:     hidden_remainder_x
      - .offset:         164
        .size:           2
        .value_kind:     hidden_remainder_y
      - .offset:         166
        .size:           2
        .value_kind:     hidden_remainder_z
      - .offset:         184
        .size:           8
        .value_kind:     hidden_global_offset_x
      - .offset:         192
        .size:           8
        .value_kind:     hidden_global_offset_y
      - .offset:         200
        .size:           8
        .value_kind:     hidden_global_offset_z
      - .offset:         208
        .size:           2
        .value_kind:     hidden_grid_dims
      - .offset:         232
        .size:           8
        .value_kind:     hidden_multigrid_sync_arg
      - .offset:         264
        .size:           4
        .value_kind:     hidden_dynamic_lds_size
    .group_segment_fixed_size: 16
    .kernarg_segment_align: 8
    .kernarg_segment_size: 400
    .language:       OpenCL C
    .language_version:
      - 2
      - 0
    .max_flat_workgroup_size: 512
    .name:           _Z10hybrid_fwd4Args
    .private_segment_fixed_size: 0
    .sgpr_count:     105
    .sgpr_spill_count: 3
    .symbol:         _Z10hybrid_fwd4Args.kd
    .uniform_work_group_size: 1
    .uses_dynamic_stack: false
    .vgpr_count:     256
    .vgpr_spill_count: 0
    .wavefront_size: 64
